# row passes: 16 consecutive rows per wave instead of rows strided by the wave count (when the grid has 2048 waves)
# baseline (speedup 1.0000x reference)
.LBB0_22:
	v_writelane_b32 v252, s52, 28
	s_nop 1
	v_writelane_b32 v252, s53, 29
	v_writelane_b32 v252, s54, 30
	v_writelane_b32 v252, s55, 31
	v_writelane_b32 v252, s56, 32
	v_writelane_b32 v252, s57, 33
	v_writelane_b32 v252, s58, 34
	v_writelane_b32 v252, s59, 35
	v_writelane_b32 v252, s60, 36
	v_writelane_b32 v252, s61, 37
	v_writelane_b32 v252, s62, 38
	v_writelane_b32 v252, s63, 39
	v_writelane_b32 v252, s64, 40
	v_writelane_b32 v252, s65, 41
	v_writelane_b32 v252, s66, 42
	v_writelane_b32 v252, s67, 43
	v_writelane_b32 v252, s38, 44
	s_nop 1
	v_writelane_b32 v252, s39, 45
	s_or_b64 exec, exec, s[36:37]
	s_add_i32 s0, 0, 0x24400
	v_mov_b32_e32 v0, s0
	s_waitcnt lgkmcnt(0)
	s_barrier
	ds_read_b32 v0, v0
	s_mov_b32 s1, 0
	s_cmp_ge_i32 s50, s51
	s_waitcnt lgkmcnt(0)
	v_readfirstlane_b32 s68, v0
	s_cbranch_scc1 .LBB0_651
	s_add_u32 s4, s48, 0x4500000
	s_addc_u32 s5, s49, 0
	s_add_u32 s28, s48, 0x4540000
	v_writelane_b32 v252, s4, 46
	s_addc_u32 s29, s49, 0
	s_mov_b32 s10, s2
	v_writelane_b32 v252, s5, 47
	s_add_u32 s4, s48, 0x4560000
	s_addc_u32 s5, s49, 0
	v_writelane_b32 v252, s4, 48
	v_mov_b32_e32 v189, 0
	v_mbcnt_lo_u32_b32 v0, -1, 0
	v_writelane_b32 v252, s5, 49
	s_add_u32 s4, s48, 0x4a00000
	s_addc_u32 s5, s49, 0
	v_writelane_b32 v252, s4, 50
	s_add_u32 s0, s48, 0x4e00000
	v_mov_b32_e32 v205, 0x358637bd
	v_writelane_b32 v252, s5, 51
	v_writelane_b32 v252, s0, 52
	s_addc_u32 s0, s49, 0
	s_add_u32 s30, s48, 0x6e00000
	s_addc_u32 s31, s49, 0
	s_add_u32 s80, s48, 0xae00000
	s_addc_u32 s81, s49, 0
	s_add_u32 s82, s48, 0xce00000
	s_addc_u32 s83, s49, 0
	s_add_u32 s88, s48, 0xee00000
	s_addc_u32 s89, s49, 0
	s_add_u32 s4, s48, 0x14000000
	v_writelane_b32 v252, s0, 53
	s_addc_u32 s5, s49, 0
	v_writelane_b32 v252, s4, 54
	v_mbcnt_hi_u32_b32 v207, -1, v0
	v_mov_b32_e32 v208, 1
	v_writelane_b32 v252, s5, 55
	s_add_u32 s4, s48, 0x17000000
	s_addc_u32 s5, s49, 0
	v_writelane_b32 v252, s4, 56
	v_mov_b32_e32 v209, 0x42800000
	v_mov_b32_e32 v210, 0xff800000
	v_writelane_b32 v252, s5, 57
	s_add_u32 s4, s48, 0x1a000000
	s_addc_u32 s5, s49, 0
	s_add_u32 s90, s48, 0x1c000000
	v_writelane_b32 v252, s4, 58
	s_addc_u32 s91, s49, 0
	v_mov_b32_e32 v211, 0x1fcf
	v_writelane_b32 v252, s5, 59
	s_add_u32 s4, s48, 0x16e00000
	s_addc_u32 s5, s49, 0
	s_add_u32 s94, s48, 0x12e00000
	v_writelane_b32 v252, s4, 60
	s_addc_u32 s95, s49, 0
	v_mov_b32_e32 v212, 0x461c4000
	v_writelane_b32 v252, s5, 61
	s_add_u32 s4, s48, 0x1ae00000
	s_addc_u32 s5, s49, 0
	v_writelane_b32 v252, s4, 62
	v_mov_b32_e32 v213, 0x37000000
	v_mov_b32_e32 v214, 0x7f800000
	v_writelane_b32 v252, s5, 63
	s_add_u32 s4, s48, 0x19e00000
	s_addc_u32 s5, s49, 0
	v_writelane_b32 v253, s4, 0
	s_movk_i32 s77, 0x300
	s_movk_i32 s33, 0x1800
	v_writelane_b32 v253, s5, 1
	s_add_u32 s4, s46, 0x4000000
	s_addc_u32 s5, s47, 0
	v_writelane_b32 v253, s4, 2
	s_movk_i32 s84, 0xa40
	s_mov_b32 s78, 0x43000000
	v_writelane_b32 v253, s5, 3
	s_add_u32 s4, s48, 0x4983000
	s_addc_u32 s5, s49, 0
	v_writelane_b32 v253, s4, 4
	s_mov_b32 s43, 0xff800000
	s_mov_b32 s34, s50
	v_writelane_b32 v253, s5, 5
	s_add_u32 s4, s48, 0x4983100
	s_addc_u32 s5, s49, 0
	v_writelane_b32 v253, s4, 6
	s_cmpk_lt_i32 s68, 0x400
	s_mov_b64 s[92:93], 0x80
	v_writelane_b32 v253, s5, 7
	s_cselect_b64 s[4:5], -1, 0
	s_lshl_b32 s69, s2, 3
	s_lshl_b32 s70, s96, 3
	s_lshl_b32 s71, s96, 4
	s_cmp_eq_u32 s70, 0x800
	s_cselect_b32 s70, 1, s70
	s_cselect_b32 s71, 2, s71
	s_cmpk_lt_i32 s68, 0x200
	v_writelane_b32 v253, s4, 8
	s_cselect_b64 s[2:3], -1, 0
	s_ashr_i32 s6, s68, 31
	v_writelane_b32 v253, s5, 9
	s_lshr_b32 s0, s6, 27
	v_writelane_b32 v253, s2, 10
	s_add_i32 s0, s68, s0
	s_nop 0
	v_writelane_b32 v253, s3, 11
	s_and_b32 s2, s0, 0xffe0
	s_sub_i32 s2, s68, s2
	s_bfe_i32 s3, s2, 0x80000
	s_bfe_u32 s3, s3, 0x3000c
	s_add_i32 s3, s2, s3
	s_and_b32 s4, s3, 0xf8
	s_sub_i32 s2, s2, s4
	s_ashr_i32 s0, s0, 5
	s_bfe_i32 s3, s3, 0x80000
	s_lshl_b32 s0, s0, 3
	s_sext_i32_i16 s3, s3
	s_sext_i32_i8 s2, s2
	s_add_i32 s8, s0, s2
	s_lshr_b32 s0, s3, 3
	s_ashr_i32 s9, s8, 31
	s_ashr_i32 s72, s3, 3
	s_bfe_i64 s[2:3], s[0:1], 0x100000
	s_mul_i32 s4, s8, 0x160000
	s_mul_hi_i32 s0, s8, 0x160000
	s_add_u32 s4, s88, s4
	s_addc_u32 s5, s89, s0
	s_add_u32 s12, s4, 0xb0000
	v_writelane_b32 v253, s4, 12
	s_addc_u32 s13, s5, 0
	s_cmpk_lt_i32 s68, 0xb00
	v_writelane_b32 v253, s5, 13
	v_writelane_b32 v253, s12, 14
	s_cselect_b64 s[4:5], -1, 0
	s_mul_hi_i32 s0, s68, 0x2e8ba2e9
	v_writelane_b32 v253, s13, 15
	v_writelane_b32 v253, s4, 16
	s_nop 1
	v_writelane_b32 v253, s5, 17
	s_lshr_b32 s4, s0, 31
	s_ashr_i32 s0, s0, 4
	s_add_i32 s0, s0, s4
	s_mul_i32 s4, s0, 0x58
	s_sub_i32 s4, s68, s4
	s_bfe_i32 s5, s4, 0x80000
	s_bfe_u32 s5, s5, 0x2000d
	s_add_i32 s5, s4, s5
	s_and_b32 s7, s5, 0xfc
	s_sub_i32 s4, s4, s7
	s_bfe_i32 s5, s5, 0x80000
	s_lshl_b32 s0, s0, 2
	s_sext_i32_i16 s5, s5
	s_sext_i32_i8 s4, s4
	s_add_i32 s12, s0, s4
	s_ashr_i32 s0, s5, 2
	v_writelane_b32 v253, s0, 18
	s_lshr_b32 s0, s5, 2
	s_bfe_i64 s[4:5], s[0:1], 0x100000
	s_lshl_b64 s[4:5], s[4:5], 19
	s_ashr_i32 s13, s12, 31
	v_writelane_b32 v253, s4, 19
	s_mov_b32 s0, s12
	s_nop 0
	v_writelane_b32 v253, s5, 20
	s_lshl_b64 s[4:5], s[12:13], 19
	v_writelane_b32 v253, s0, 21
	s_add_u32 s4, s30, s4
	s_addc_u32 s5, s31, s5
	v_writelane_b32 v253, s1, 22
	s_add_u32 s12, s4, 0x40000
	v_writelane_b32 v253, s4, 23
	s_addc_u32 s13, s5, 0
	s_mov_b32 s0, s8
	v_writelane_b32 v253, s5, 24
	v_writelane_b32 v253, s12, 25
	s_nop 1
	v_writelane_b32 v253, s13, 26
	v_readlane_b32 s12, v252, 28
	v_readlane_b32 s20, v252, 36
	v_readlane_b32 s21, v252, 37
	s_cmp_lg_u64 s[20:21], 0
	s_cselect_b64 s[4:5], -1, 0
	v_writelane_b32 v253, s4, 27
	s_lshl_b64 s[2:3], s[2:3], 19
	v_readlane_b32 s13, v252, 29
	v_writelane_b32 v253, s5, 28
	v_writelane_b32 v253, s2, 29
	v_readlane_b32 s14, v252, 30
	v_readlane_b32 s15, v252, 31
	v_writelane_b32 v253, s3, 30
	s_lshl_b64 s[2:3], s[8:9], 19
	v_writelane_b32 v253, s0, 31
	s_add_u32 s2, s30, s2
	s_addc_u32 s3, s31, s3
	v_writelane_b32 v253, s1, 32
	s_add_u32 s4, s2, 0x40000
	v_writelane_b32 v253, s2, 33
	s_addc_u32 s5, s3, 0
	s_cmpk_lt_i32 s68, 0x600
	v_writelane_b32 v253, s3, 34
	v_writelane_b32 v253, s4, 35
	s_cselect_b64 s[2:3], -1, 0
	s_mul_hi_i32 s0, s68, 0x2aaaaaab
	v_writelane_b32 v253, s5, 36
	v_writelane_b32 v253, s2, 37
	v_readlane_b32 s16, v252, 32
	v_readlane_b32 s17, v252, 33
	v_writelane_b32 v253, s3, 38
	s_lshr_b32 s2, s0, 31
	s_ashr_i32 s0, s0, 3
	s_add_i32 s7, s0, s2
	s_mul_i32 s0, s7, 48
	s_sub_i32 s8, s68, s0
	s_bfe_i32 s0, s8, 0x80000
	s_lshr_b32 s9, s0, 7
	s_bfe_u32 s0, s9, 0x20006
	s_add_i32 s0, s8, s0
	s_bfe_i32 s2, s0, 0x80000
	s_and_b32 s0, s0, 0xfc
	s_sub_i32 s0, s8, s0
	s_sext_i32_i16 s2, s2
	s_sext_i32_i8 s0, s0
	s_lshl_b32 s3, s7, 2
	s_add_i32 s4, s3, s0
	s_ashr_i32 s0, s2, 2
	v_writelane_b32 v253, s0, 39
	s_lshr_b32 s0, s2, 2
	s_bfe_i64 s[2:3], s[0:1], 0x100000
	s_lshl_b64 s[2:3], s[2:3], 19
	s_ashr_i32 s5, s4, 31
	v_writelane_b32 v253, s2, 40
	s_mov_b32 s0, s4
	v_readlane_b32 s18, v252, 34
	v_writelane_b32 v253, s3, 41
	s_lshl_b64 s[2:3], s[4:5], 19
	s_add_u32 s2, s30, s2
	v_writelane_b32 v253, s0, 42
	s_addc_u32 s3, s31, s3
	s_add_u32 s4, s2, 0x40000
	v_writelane_b32 v253, s1, 43
	v_writelane_b32 v253, s2, 44
	s_addc_u32 s5, s3, 0
	s_cmpk_lt_i32 s10, 0x800
	v_writelane_b32 v253, s3, 45
	v_writelane_b32 v253, s4, 46
	s_cselect_b64 s[2:3], -1, 0
	s_lshr_b32 s0, s6, 22
	v_writelane_b32 v253, s5, 47
	s_add_i32 s0, s68, s0
	v_writelane_b32 v253, s2, 48
	s_and_b32 s4, s0, 0xfffffc00
	s_sub_i32 s4, s68, s4
	v_writelane_b32 v253, s3, 49
	s_ashr_i32 s2, s0, 10
	s_ashr_i32 s3, s2, 31
	s_ashr_i32 s5, s4, 31
	s_lshl_b64 s[2:3], s[2:3], 17
	s_mov_b32 s0, s4
	s_lshl_b64 s[4:5], s[4:5], 17
	s_add_u32 s4, s88, s4
	v_writelane_b32 v253, s0, 50
	s_addc_u32 s5, s89, s5
	s_add_u32 s2, s28, s2
	v_writelane_b32 v253, s1, 51
	v_writelane_b32 v253, s28, 52
	s_addc_u32 s3, s29, s3
	s_add_u32 s12, s4, 0x10000
	v_writelane_b32 v253, s29, 53
	s_addc_u32 s13, s5, 0
	v_writelane_b32 v253, s12, 54
	v_readlane_b32 s19, v252, 35
	v_readlane_b32 s22, v252, 38
	v_writelane_b32 v253, s13, 55
	s_add_u32 s12, s2, 0x10000
	v_writelane_b32 v253, s2, 56
	s_addc_u32 s13, s3, 0
	v_readlane_b32 s23, v252, 39
	v_writelane_b32 v253, s3, 57
	v_writelane_b32 v253, s12, 58
	s_add_u32 s2, s4, 0x10080
	v_readlane_b32 s24, v252, 40
	v_writelane_b32 v253, s13, 59
	v_writelane_b32 v253, s4, 60
	s_addc_u32 s3, s5, 0
	s_cmpk_lt_i32 s68, 0x900
	v_writelane_b32 v253, s5, 61
	v_writelane_b32 v253, s2, 62
	v_readlane_b32 s25, v252, 41
	v_readlane_b32 s26, v252, 42
	v_writelane_b32 v253, s3, 63
	s_cselect_b64 s[2:3], -1, 0
	v_writelane_b32 v254, s2, 0
	v_readlane_b32 s27, v252, 43
	v_readlane_b32 s12, v252, 12
	v_writelane_b32 v254, s3, 1
	s_add_u32 s2, s48, 0xee00300
	s_addc_u32 s3, s49, 0
	v_writelane_b32 v254, s2, 2
	s_cmpk_lt_i32 s68, 0x300
	v_readlane_b32 s13, v252, 13
	v_writelane_b32 v254, s3, 3
	s_cselect_b64 s[2:3], -1, 0
	s_bfe_u32 s0, s9, 0x30005
	v_writelane_b32 v254, s2, 4
	s_add_i32 s0, s8, s0
	v_readlane_b32 s14, v252, 14
	v_writelane_b32 v254, s3, 5
	s_and_b32 s2, s0, 0xf8
	s_sub_i32 s2, s8, s2
	s_bfe_i32 s0, s0, 0x80000
	s_lshl_b32 s3, s7, 3
	s_sext_i32_i16 s0, s0
	s_sext_i32_i8 s2, s2
	s_add_i32 s8, s3, s2
	s_ashr_i32 s73, s0, 3
	s_lshr_b32 s0, s0, 3
	v_readlane_b32 s15, v252, 15
	v_readlane_b32 s16, v252, 16
	v_readlane_b32 s17, v252, 17
	v_readlane_b32 s18, v252, 18
	v_readlane_b32 s19, v252, 19
	s_cmp_lg_u64 s[12:13], 0
	s_cselect_b64 s[2:3], -1, 0
	v_readlane_b32 s12, v252, 0
	v_writelane_b32 v254, s2, 6
	v_readlane_b32 s18, v252, 6
	v_readlane_b32 s19, v252, 7
	v_writelane_b32 v254, s3, 7
	s_add_u32 s2, s18, 0x1000
	s_addc_u32 s3, s19, 0
	v_writelane_b32 v254, s2, 8
	v_readlane_b32 s4, v252, 8
	v_readlane_b32 s5, v252, 9
	v_writelane_b32 v254, s3, 9
	s_add_u32 s2, s18, 0x1400
	s_addc_u32 s3, s19, 0
	v_writelane_b32 v254, s2, 10
	v_readlane_b32 s6, v252, 10
	v_readlane_b32 s7, v252, 11
	v_writelane_b32 v254, s3, 11
	s_add_u32 s2, s18, 0x1800
	s_addc_u32 s3, s19, 0
	v_writelane_b32 v254, s2, 12
	v_readlane_b32 s13, v252, 1
	v_readlane_b32 s14, v252, 2
	v_writelane_b32 v254, s3, 13
	s_add_u32 s2, s18, 0x1c00
	s_addc_u32 s3, s19, 0
	v_writelane_b32 v254, s2, 14
	s_cmp_lg_u64 s[46:47], 0
	v_readlane_b32 s15, v252, 3
	v_writelane_b32 v254, s3, 15
	s_cselect_b64 s[2:3], -1, 0
	v_writelane_b32 v254, s2, 16
	s_cmpk_lt_i32 s10, 0x2270
	s_mov_b32 s28, 0x8000
	v_writelane_b32 v254, s3, 17
	s_cselect_b64 s[2:3], -1, 0
	v_writelane_b32 v254, s2, 18
	s_cmpk_lt_i32 s10, 0x400
	s_movk_i32 s29, 0xc0
	v_writelane_b32 v254, s3, 19
	s_cselect_b64 s[2:3], -1, 0
	v_writelane_b32 v254, s2, 20
	s_cmpk_lt_i32 s10, 0x980
	v_readlane_b32 s20, v252, 20
	v_writelane_b32 v254, s3, 21
	s_cselect_b64 s[2:3], -1, 0
	v_writelane_b32 v254, s2, 22
	s_cmpk_lt_i32 s10, 0x1000
	v_readlane_b32 s21, v252, 21
	v_writelane_b32 v254, s3, 23
	s_cselect_b64 s[2:3], -1, 0
	v_writelane_b32 v254, s2, 24
	s_cmp_lg_u64 s[4:5], 0
	v_readlane_b32 s22, v252, 22
	v_writelane_b32 v254, s3, 25
	s_cselect_b64 s[2:3], -1, 0
	v_writelane_b32 v254, s2, 26
	s_ashr_i32 s9, s8, 31
	v_readlane_b32 s23, v252, 23
	v_writelane_b32 v254, s3, 27
	s_bfe_i64 s[2:3], s[0:1], 0x100000
	s_lshl_b64 s[2:3], s[2:3], 19
	v_writelane_b32 v254, s2, 28
	s_mov_b32 s0, s8
	v_readlane_b32 s24, v252, 24
	v_writelane_b32 v254, s3, 29
	v_writelane_b32 v254, s0, 30
	s_lshl_b64 s[2:3], s[8:9], 19
	s_add_u32 s2, s30, s2
	v_writelane_b32 v254, s1, 31
	v_writelane_b32 v254, s30, 32
	s_addc_u32 s3, s31, s3
	s_add_u32 s4, s2, 0x40000
	v_writelane_b32 v254, s31, 33
	v_writelane_b32 v254, s2, 34
	s_addc_u32 s5, s3, 0
	s_add_u32 s0, s48, 0x2060100
	v_writelane_b32 v254, s3, 35
	v_writelane_b32 v254, s4, 36
	s_mov_b32 s30, 0x800000
	s_movk_i32 s31, 0x7fff
	v_writelane_b32 v254, s5, 37
	v_writelane_b32 v254, s0, 38
	s_addc_u32 s0, s49, 0
	s_add_u32 s2, s48, 0x6e00100
	v_writelane_b32 v254, s0, 39
	s_addc_u32 s3, s49, 0
	v_writelane_b32 v254, s2, 40
	s_lshl_b32 s0, s10, 8
	s_ashr_i32 s11, s10, 31
	v_writelane_b32 v254, s3, 41
	v_writelane_b32 v254, s0, 42
	s_lshl_b32 s0, s10, 7
	s_lshl_b32 s74, s96, 8
	v_writelane_b32 v254, s0, 43
	s_lshl_b32 s75, s96, 7
	s_lshl_b32 s0, s68, 8
	s_lshl_b32 s76, s10, 9
	s_lshl_b32 s87, s96, 9
	s_lshl_b64 s[2:3], s[10:11], 13
	v_writelane_b32 v254, s0, 44
	s_add_u32 s0, s48, s2
	s_addc_u32 s2, s49, s3
	s_add_u32 s4, s0, 0x4e00000
	s_addc_u32 s5, s2, 0
	v_writelane_b32 v254, s4, 45
	s_ashr_i32 s97, s96, 31
	s_lshl_b64 s[2:3], s[96:97], 13
	v_writelane_b32 v254, s5, 46
	v_writelane_b32 v254, s2, 47
	s_mov_b32 s0, s10
	v_readlane_b32 s25, v252, 25
	v_writelane_b32 v254, s3, 48
	v_writelane_b32 v254, s0, 49
	s_lshl_b64 s[2:3], s[10:11], 14
	v_readlane_b32 s26, v252, 26
	v_writelane_b32 v254, s1, 50
	s_add_u32 s0, s6, s2
	s_addc_u32 s2, s7, s3
	s_add_u32 s4, s0, 16
	s_addc_u32 s5, s2, 0
	v_writelane_b32 v254, s4, 51
	v_cmp_eq_u32_e64 s[2:3], 0, v204
	s_brev_b32 s0, 1
	v_writelane_b32 v254, s5, 52
	v_writelane_b32 v254, s2, 53
	s_add_i32 s85, 0, 0x24404
	s_add_i32 s86, 0, 0x2440c
	v_writelane_b32 v254, s3, 54
	s_lshl_b64 s[2:3], s[96:97], 14
	v_writelane_b32 v254, s2, 55
	v_readlane_b32 s27, v252, 27
	v_readlane_b32 s16, v252, 4
	v_writelane_b32 v254, s3, 56
	v_writelane_b32 v254, s0, 57
	v_readlane_b32 s17, v252, 5
	s_nop 0
	v_writelane_b32 v255, s7, 0
	v_writelane_b32 v255, s8, 1
	v_writelane_b32 v255, s9, 2
	v_writelane_b32 v255, s10, 3
	v_writelane_b32 v255, s11, 4
	v_writelane_b32 v255, s12, 5
	v_writelane_b32 v255, s13, 6
	v_writelane_b32 v255, s14, 7
	v_writelane_b32 v255, s15, 8
	v_writelane_b32 v255, s68, 9
	v_writelane_b32 v255, s69, 10
	v_writelane_b32 v255, s70, 11
	v_writelane_b32 v255, s71, 12
	v_writelane_b32 v255, s72, 13
	v_writelane_b32 v254, s1, 58
	v_writelane_b32 v255, s73, 14
	v_writelane_b32 v254, s2, 59
	v_writelane_b32 v255, s74, 15
	v_writelane_b32 v254, s3, 60
	v_writelane_b32 v255, s75, 16
	v_writelane_b32 v254, s4, 61
	v_writelane_b32 v255, s76, 17
	v_writelane_b32 v254, s5, 62
	v_writelane_b32 v255, s85, 18
	v_writelane_b32 v254, s6, 63
	v_writelane_b32 v255, s86, 19
	s_branch .LBB0_25

.LBB0_93:
	v_mov_b32_e32 v0, v204
	s_nop 0
	v_ashrrev_i32_e32 v0, 6, v0
	v_add_u32_e32 v16, s69, v0
	s_cmp_eq_u32 s70, 1
	s_cbranch_scc0 .Lrm0_old
	v_lshlrev_b32_e32 v16, 4, v16
	v_add_u32_e32 v124, 16, v16
	s_branch .Lrm0_done
.Lrm0_old:
	v_mov_b32_e32 v124, s28
.Lrm0_done:
	v_add_u32_e32 v125, -1, v124
	v_mov_b32_e32 v0, v204
	v_cmp_gt_i32_e32 vcc, v124, v16
	s_and_saveexec_b64 s[2:3], vcc
	s_cbranch_execz .LBB0_96
	v_readlane_b32 s4, v255, 21
	v_readlane_b32 s5, v255, 22
	s_lshl_b32 s4, s4, 10
	s_ashr_i32 s5, s4, 31
	v_readlane_b32 s8, v252, 0
	s_lshl_b64 s[4:5], s[4:5], 2
	v_readlane_b32 s10, v252, 2
	v_readlane_b32 s11, v252, 3
	v_readlane_b32 s9, v252, 1
	s_add_u32 s4, s8, s4
	v_ashrrev_i32_e32 v17, 31, v16
	v_readlane_b32 s10, v253, 2
	v_lshlrev_b32_e32 v0, 2, v0
	s_addc_u32 s5, s9, s5
	v_lshlrev_b64 v[2:3], 11, v[16:17]
	v_readlane_b32 s11, v253, 3
	v_and_b32_e32 v6, 0xfc, v0
	v_readlane_b32 s8, v253, 0
	v_add_u32_e32 v17, s70, v16
	v_lshl_add_u64 v[4:5], s[10:11], 0, v[2:3]
	v_lshlrev_b32_e32 v188, 1, v6
	v_readlane_b32 s9, v253, 1
	v_cmp_gt_i32_e32 vcc, v124, v17
	v_lshl_add_u64 v[0:1], v[4:5], 0, v[188:189]
	v_lshl_add_u64 v[2:3], s[8:9], 0, v[2:3]
	v_cndmask_b32_e32 v18, v16, v17, vcc
	v_lshl_add_u64 v[2:3], v[2:3], 0, v[188:189]
	global_load_dwordx2 v[52:53], v[0:1], off
	global_load_dwordx2 v[48:49], v[0:1], off offset:512
	global_load_dwordx2 v[44:45], v[0:1], off offset:1024
	global_load_dwordx2 v[40:41], v[0:1], off offset:1536
	global_load_dwordx2 v[54:55], v[2:3], off
	global_load_dwordx2 v[50:51], v[2:3], off offset:512
	global_load_dwordx2 v[46:47], v[2:3], off offset:1024
	global_load_dwordx2 v[42:43], v[2:3], off offset:1536
	v_ashrrev_i32_e32 v19, 31, v18
	v_lshlrev_b64 v[22:23], 11, v[18:19]
	v_lshl_add_u64 v[18:19], s[8:9], 0, v[22:23]
	v_lshl_add_u64 v[22:23], s[10:11], 0, v[22:23]
	v_lshlrev_b32_e32 v12, 2, v6
	v_lshl_add_u64 v[26:27], v[18:19], 0, v[188:189]
	v_lshl_add_u64 v[22:23], v[22:23], 0, v[188:189]
	global_load_dwordx4 v[0:3], v12, s[4:5]
	global_load_dwordx4 v[4:7], v12, s[4:5] offset:1024
	global_load_dwordx4 v[8:11], v12, s[4:5] offset:2048
	s_nop 0
	global_load_dwordx4 v[12:15], v12, s[4:5] offset:3072
	s_nop 0
	global_load_dwordx2 v[18:19], v[26:27], off offset:1536
	global_load_dwordx2 v[20:21], v[26:27], off offset:1024
	global_load_dwordx2 v[24:25], v[26:27], off offset:512
	s_nop 0
	global_load_dwordx2 v[26:27], v[26:27], off
	s_nop 0
	global_load_dwordx2 v[30:31], v[22:23], off offset:1536
	global_load_dwordx2 v[34:35], v[22:23], off offset:1024
	global_load_dwordx2 v[36:37], v[22:23], off offset:512
	global_load_dwordx2 v[38:39], v[22:23], off
	v_readlane_b32 s4, v254, 32
	v_readlane_b32 s5, v254, 33
	v_lshl_add_u64 v[22:23], s[10:11], 0, v[188:189]
	v_lshl_add_u64 v[28:29], s[8:9], 0, v[188:189]
	v_lshl_add_u64 v[32:33], s[4:5], 0, v[188:189]
	s_mov_b64 s[4:5], 0
	v_readlane_b32 s12, v252, 4
	v_readlane_b32 s13, v252, 5
	v_readlane_b32 s14, v252, 6
	v_readlane_b32 s15, v252, 7
	s_waitcnt vmcnt(0)
.LBB0_95:
	v_add_u32_e32 v104, s71, v16
	v_cmp_gt_i32_e32 vcc, v124, v104
	s_nop 1
	v_cndmask_b32_e32 v56, v16, v104, vcc
	v_ashrrev_i32_e32 v57, 31, v56
	v_lshlrev_b64 v[56:57], 11, v[56:57]
	v_lshl_add_u64 v[62:63], v[22:23], 0, v[56:57]
	v_lshl_add_u64 v[70:71], v[28:29], 0, v[56:57]
	global_load_dwordx2 v[56:57], v[62:63], off
	global_load_dwordx2 v[58:59], v[62:63], off offset:512
	global_load_dwordx2 v[60:61], v[62:63], off offset:1024
	s_nop 0
	global_load_dwordx2 v[62:63], v[62:63], off offset:1536
	s_nop 0
	global_load_dwordx2 v[64:65], v[70:71], off
	global_load_dwordx2 v[66:67], v[70:71], off offset:512
	global_load_dwordx2 v[68:69], v[70:71], off offset:1024
	s_nop 0
	global_load_dwordx2 v[70:71], v[70:71], off offset:1536
	v_and_b32_e32 v17, 64, v207
	v_add_u32_e32 v17, 64, v17
	v_xor_b32_e32 v72, 32, v207
	v_cmp_lt_i32_e32 vcc, v72, v17
	s_waitcnt vmcnt(24)
	v_and_b32_e32 v73, 0xffff0000, v53
	v_lshlrev_b32_e32 v78, 16, v52
	v_cndmask_b32_e32 v72, v207, v72, vcc
	v_lshlrev_b32_e32 v105, 2, v72
	v_xor_b32_e32 v72, 16, v207
	v_cmp_lt_i32_e32 vcc, v72, v17
	v_and_b32_e32 v79, 0xffff0000, v52
	v_lshlrev_b32_e32 v52, 16, v54
	v_cndmask_b32_e32 v72, v207, v72, vcc
	v_lshlrev_b32_e32 v106, 2, v72
	v_xor_b32_e32 v72, 8, v207
	v_cmp_lt_i32_e32 vcc, v72, v17
	v_lshlrev_b32_e32 v74, 16, v55
	v_and_b32_e32 v75, 0xffff0000, v55
	v_cndmask_b32_e32 v72, v207, v72, vcc
	v_lshlrev_b32_e32 v107, 2, v72
	v_xor_b32_e32 v72, 4, v207
	v_cmp_lt_i32_e32 vcc, v72, v17
	v_pk_mul_f32 v[76:77], v[74:75], v[74:75]
	v_lshlrev_b32_e32 v80, 16, v49
	v_cndmask_b32_e32 v72, v207, v72, vcc
	v_lshlrev_b32_e32 v108, 2, v72
	v_xor_b32_e32 v72, 2, v207
	v_cmp_lt_i32_e32 vcc, v72, v17
	s_waitcnt lgkmcnt(0)
	v_and_b32_e32 v81, 0xffff0000, v49
	v_lshlrev_b32_e32 v86, 16, v48
	v_cndmask_b32_e32 v72, v207, v72, vcc
	v_lshlrev_b32_e32 v109, 2, v72
	v_xor_b32_e32 v72, 1, v207
	v_cmp_lt_i32_e32 vcc, v72, v17
	v_and_b32_e32 v87, 0xffff0000, v48
	v_lshlrev_b32_e32 v48, 16, v50
	v_cndmask_b32_e32 v17, v207, v72, vcc
	v_lshlrev_b32_e32 v72, 16, v53
	v_and_b32_e32 v53, 0xffff0000, v54
	v_pk_mul_f32 v[54:55], v[52:53], v[52:53]
	v_and_b32_e32 v49, 0xffff0000, v50
	v_add_f32_e32 v54, v54, v55
	v_add_f32_e32 v54, v76, v54
	v_lshlrev_b32_e32 v82, 16, v51
	v_and_b32_e32 v83, 0xffff0000, v51
	v_pk_mul_f32 v[50:51], v[48:49], v[48:49]
	v_add_f32_e32 v54, v77, v54
	v_add_f32_e32 v50, v50, v54
	v_pk_mul_f32 v[84:85], v[82:83], v[82:83]
	v_add_f32_e32 v50, v51, v50
	v_lshlrev_b32_e32 v88, 16, v45
	v_and_b32_e32 v89, 0xffff0000, v45
	v_lshlrev_b32_e32 v94, 16, v44
	v_and_b32_e32 v95, 0xffff0000, v44
	v_lshlrev_b32_e32 v44, 16, v46
	v_and_b32_e32 v45, 0xffff0000, v46
	v_add_f32_e32 v50, v84, v50
	v_lshlrev_b32_e32 v90, 16, v47
	v_and_b32_e32 v91, 0xffff0000, v47
	v_pk_mul_f32 v[46:47], v[44:45], v[44:45]
	v_add_f32_e32 v50, v85, v50
	v_add_f32_e32 v46, v46, v50
	v_pk_mul_f32 v[92:93], v[90:91], v[90:91]
	v_add_f32_e32 v46, v47, v46
	v_lshlrev_b32_e32 v96, 16, v41
	v_and_b32_e32 v97, 0xffff0000, v41
	v_lshlrev_b32_e32 v102, 16, v40
	v_and_b32_e32 v103, 0xffff0000, v40
	v_lshlrev_b32_e32 v40, 16, v42
	v_and_b32_e32 v41, 0xffff0000, v42
	v_add_f32_e32 v46, v92, v46
	v_lshlrev_b32_e32 v98, 16, v43
	v_and_b32_e32 v99, 0xffff0000, v43
	v_pk_mul_f32 v[42:43], v[40:41], v[40:41]
	v_add_f32_e32 v46, v93, v46
	v_add_f32_e32 v42, v42, v46
	v_pk_mul_f32 v[100:101], v[98:99], v[98:99]
	v_add_f32_e32 v42, v43, v42
	v_add_f32_e32 v42, v100, v42
	v_add_f32_e32 v42, v101, v42
	ds_bpermute_b32 v43, v105, v42
	v_lshlrev_b32_e32 v17, 2, v17
	s_waitcnt lgkmcnt(0)
	v_add_f32_e32 v42, v42, v43
	ds_bpermute_b32 v43, v106, v42
	s_waitcnt lgkmcnt(0)
	v_add_f32_e32 v42, v42, v43
	ds_bpermute_b32 v43, v107, v42
	s_waitcnt lgkmcnt(0)
	v_add_f32_e32 v42, v42, v43
	ds_bpermute_b32 v43, v108, v42
	s_waitcnt lgkmcnt(0)
	v_add_f32_e32 v42, v42, v43
	ds_bpermute_b32 v43, v109, v42
	s_waitcnt lgkmcnt(0)
	v_add_f32_e32 v42, v42, v43
	ds_bpermute_b32 v17, v17, v42
	s_waitcnt lgkmcnt(0)
	v_add_f32_e32 v17, v42, v17
	v_fmamk_f32 v17, v17, 0x3a800000, v205
	v_cmp_gt_f32_e32 vcc, s30, v17
	v_mul_f32_e32 v42, 0x4b800000, v17
	s_nop 0
	v_cndmask_b32_e32 v17, v17, v42, vcc
	v_rsq_f32_e32 v17, v17
	s_nop 0
	v_mul_f32_e32 v42, 0x45800000, v17
	v_cndmask_b32_e32 v42, v17, v42, vcc
	v_pk_mul_f32 v[46:47], v[42:43], v[52:53] op_sel_hi:[0,1]
	v_pk_mul_f32 v[50:51], v[42:43], v[74:75] op_sel_hi:[0,1]
	v_ashrrev_i32_e32 v17, 31, v16
	v_pk_fma_f32 v[46:47], v[0:1], v[46:47], v[78:79]
	v_pk_fma_f32 v[50:51], v[2:3], v[50:51], v[72:73]
	v_pk_mul_f32 v[48:49], v[42:43], v[48:49] op_sel_hi:[0,1]
	v_pk_mul_f32 v[52:53], v[42:43], v[82:83] op_sel_hi:[0,1]
	v_pk_mul_f32 v[44:45], v[42:43], v[44:45] op_sel_hi:[0,1]
	v_pk_mul_f32 v[54:55], v[42:43], v[90:91] op_sel_hi:[0,1]
	v_pk_mul_f32 v[40:41], v[42:43], v[40:41] op_sel_hi:[0,1]
	v_pk_mul_f32 v[42:43], v[42:43], v[98:99] op_sel_hi:[0,1]
	v_lshlrev_b64 v[16:17], 11, v[16:17]
	v_pk_fma_f32 v[48:49], v[4:5], v[48:49], v[86:87]
	v_pk_fma_f32 v[52:53], v[6:7], v[52:53], v[80:81]
	v_pk_fma_f32 v[44:45], v[8:9], v[44:45], v[94:95]
	v_pk_fma_f32 v[54:55], v[10:11], v[54:55], v[88:89]
	v_pk_fma_f32 v[40:41], v[12:13], v[40:41], v[102:103]
	v_pk_fma_f32 v[42:43], v[14:15], v[42:43], v[96:97]
	v_lshl_add_u64 v[16:17], v[32:33], 0, v[16:17]
	v_cvt_pk_bf16_f32 v46, v46, v47
	v_cvt_pk_bf16_f32 v47, v50, v51
	global_store_dwordx2 v[16:17], v[46:47], off
	v_cvt_pk_bf16_f32 v46, v48, v49
	v_cvt_pk_bf16_f32 v47, v52, v53
	v_cvt_pk_bf16_f32 v44, v44, v45
	v_cvt_pk_bf16_f32 v45, v54, v55
	v_cvt_pk_bf16_f32 v40, v40, v41
	v_cvt_pk_bf16_f32 v41, v42, v43
	global_store_dwordx2 v[16:17], v[46:47], off offset:512
	global_store_dwordx2 v[16:17], v[44:45], off offset:1024
	global_store_dwordx2 v[16:17], v[40:41], off offset:1536
	v_subrev_u32_e32 v16, s70, v104
	v_cmp_lt_i32_e32 vcc, v125, v16
	s_or_b64 s[4:5], vcc, s[4:5]
	s_andn2_b64 exec, exec, s[4:5]
	s_cbranch_execz .LBB0_96
.Lrp95_top1:
	v_add_u32_e32 v104, s71, v16
	v_cmp_gt_i32_e32 vcc, v124, v104
	s_nop 1
	v_cndmask_b32_e32 v52, v16, v104, vcc
	v_ashrrev_i32_e32 v53, 31, v52
	v_lshlrev_b64 v[52:53], 11, v[52:53]
	v_lshl_add_u64 v[40:41], v[22:23], 0, v[52:53]
	v_lshl_add_u64 v[42:43], v[28:29], 0, v[52:53]
	global_load_dwordx2 v[52:53], v[40:41], off
	global_load_dwordx2 v[48:49], v[40:41], off offset:512
	global_load_dwordx2 v[44:45], v[40:41], off offset:1024
	s_nop 0
	global_load_dwordx2 v[40:41], v[40:41], off offset:1536
	s_nop 0
	global_load_dwordx2 v[54:55], v[42:43], off
	global_load_dwordx2 v[50:51], v[42:43], off offset:512
	global_load_dwordx2 v[46:47], v[42:43], off offset:1024
	s_nop 0
	global_load_dwordx2 v[42:43], v[42:43], off offset:1536
	v_and_b32_e32 v17, 64, v207
	v_add_u32_e32 v17, 64, v17
	v_xor_b32_e32 v72, 32, v207
	v_cmp_lt_i32_e32 vcc, v72, v17
	s_waitcnt vmcnt(24)
	v_and_b32_e32 v73, 0xffff0000, v39
	v_lshlrev_b32_e32 v78, 16, v38
	v_cndmask_b32_e32 v72, v207, v72, vcc
	v_lshlrev_b32_e32 v105, 2, v72
	v_xor_b32_e32 v72, 16, v207
	v_cmp_lt_i32_e32 vcc, v72, v17
	v_and_b32_e32 v79, 0xffff0000, v38
	v_lshlrev_b32_e32 v38, 16, v26
	v_cndmask_b32_e32 v72, v207, v72, vcc
	v_lshlrev_b32_e32 v106, 2, v72
	v_xor_b32_e32 v72, 8, v207
	v_cmp_lt_i32_e32 vcc, v72, v17
	v_lshlrev_b32_e32 v74, 16, v27
	v_and_b32_e32 v75, 0xffff0000, v27
	v_cndmask_b32_e32 v72, v207, v72, vcc
	v_lshlrev_b32_e32 v107, 2, v72
	v_xor_b32_e32 v72, 4, v207
	v_cmp_lt_i32_e32 vcc, v72, v17
	v_pk_mul_f32 v[76:77], v[74:75], v[74:75]
	v_lshlrev_b32_e32 v80, 16, v37
	v_cndmask_b32_e32 v72, v207, v72, vcc
	v_lshlrev_b32_e32 v108, 2, v72
	v_xor_b32_e32 v72, 2, v207
	v_cmp_lt_i32_e32 vcc, v72, v17
	s_waitcnt lgkmcnt(0)
	v_and_b32_e32 v81, 0xffff0000, v37
	v_lshlrev_b32_e32 v86, 16, v36
	v_cndmask_b32_e32 v72, v207, v72, vcc
	v_lshlrev_b32_e32 v109, 2, v72
	v_xor_b32_e32 v72, 1, v207
	v_cmp_lt_i32_e32 vcc, v72, v17
	v_and_b32_e32 v87, 0xffff0000, v36
	v_lshlrev_b32_e32 v36, 16, v24
	v_cndmask_b32_e32 v17, v207, v72, vcc
	v_lshlrev_b32_e32 v72, 16, v39
	v_and_b32_e32 v39, 0xffff0000, v26
	v_pk_mul_f32 v[26:27], v[38:39], v[38:39]
	v_and_b32_e32 v37, 0xffff0000, v24
	v_add_f32_e32 v26, v26, v27
	v_add_f32_e32 v26, v76, v26
	v_lshlrev_b32_e32 v82, 16, v25
	v_and_b32_e32 v83, 0xffff0000, v25
	v_pk_mul_f32 v[24:25], v[36:37], v[36:37]
	v_add_f32_e32 v26, v77, v26
	v_add_f32_e32 v24, v24, v26
	v_pk_mul_f32 v[84:85], v[82:83], v[82:83]
	v_add_f32_e32 v24, v25, v24
	v_lshlrev_b32_e32 v88, 16, v35
	v_and_b32_e32 v89, 0xffff0000, v35
	v_lshlrev_b32_e32 v94, 16, v34
	v_and_b32_e32 v95, 0xffff0000, v34
	v_lshlrev_b32_e32 v34, 16, v20
	v_and_b32_e32 v35, 0xffff0000, v20
	v_add_f32_e32 v24, v84, v24
	v_lshlrev_b32_e32 v90, 16, v21
	v_and_b32_e32 v91, 0xffff0000, v21
	v_pk_mul_f32 v[20:21], v[34:35], v[34:35]
	v_add_f32_e32 v24, v85, v24
	v_add_f32_e32 v20, v20, v24
	v_pk_mul_f32 v[92:93], v[90:91], v[90:91]
	v_add_f32_e32 v20, v21, v20
	v_lshlrev_b32_e32 v96, 16, v31
	v_and_b32_e32 v97, 0xffff0000, v31
	v_lshlrev_b32_e32 v102, 16, v30
	v_and_b32_e32 v103, 0xffff0000, v30
	v_lshlrev_b32_e32 v30, 16, v18
	v_and_b32_e32 v31, 0xffff0000, v18
	v_add_f32_e32 v20, v92, v20
	v_lshlrev_b32_e32 v98, 16, v19
	v_and_b32_e32 v99, 0xffff0000, v19
	v_pk_mul_f32 v[18:19], v[30:31], v[30:31]
	v_add_f32_e32 v20, v93, v20
	v_add_f32_e32 v18, v18, v20
	v_pk_mul_f32 v[100:101], v[98:99], v[98:99]
	v_add_f32_e32 v18, v19, v18
	v_add_f32_e32 v18, v100, v18
	v_add_f32_e32 v18, v101, v18
	ds_bpermute_b32 v19, v105, v18
	v_lshlrev_b32_e32 v17, 2, v17
	s_waitcnt lgkmcnt(0)
	v_add_f32_e32 v18, v18, v19
	ds_bpermute_b32 v19, v106, v18
	s_waitcnt lgkmcnt(0)
	v_add_f32_e32 v18, v18, v19
	ds_bpermute_b32 v19, v107, v18
	s_waitcnt lgkmcnt(0)
	v_add_f32_e32 v18, v18, v19
	ds_bpermute_b32 v19, v108, v18
	s_waitcnt lgkmcnt(0)
	v_add_f32_e32 v18, v18, v19
	ds_bpermute_b32 v19, v109, v18
	s_waitcnt lgkmcnt(0)
	v_add_f32_e32 v18, v18, v19
	ds_bpermute_b32 v17, v17, v18
	s_waitcnt lgkmcnt(0)
	v_add_f32_e32 v17, v18, v17
	v_fmamk_f32 v17, v17, 0x3a800000, v205
	v_cmp_gt_f32_e32 vcc, s30, v17
	v_mul_f32_e32 v18, 0x4b800000, v17
	s_nop 0
	v_cndmask_b32_e32 v17, v17, v18, vcc
	v_rsq_f32_e32 v17, v17
	s_nop 0
	v_mul_f32_e32 v18, 0x45800000, v17
	v_cndmask_b32_e32 v18, v17, v18, vcc
	v_pk_mul_f32 v[20:21], v[18:19], v[38:39] op_sel_hi:[0,1]
	v_pk_mul_f32 v[24:25], v[18:19], v[74:75] op_sel_hi:[0,1]
	v_ashrrev_i32_e32 v17, 31, v16
	v_pk_fma_f32 v[20:21], v[0:1], v[20:21], v[78:79]
	v_pk_fma_f32 v[24:25], v[2:3], v[24:25], v[72:73]
	v_pk_mul_f32 v[36:37], v[18:19], v[36:37] op_sel_hi:[0,1]
	v_pk_mul_f32 v[38:39], v[18:19], v[82:83] op_sel_hi:[0,1]
	v_pk_mul_f32 v[34:35], v[18:19], v[34:35] op_sel_hi:[0,1]
	v_pk_mul_f32 v[26:27], v[18:19], v[90:91] op_sel_hi:[0,1]
	v_pk_mul_f32 v[30:31], v[18:19], v[30:31] op_sel_hi:[0,1]
	v_pk_mul_f32 v[18:19], v[18:19], v[98:99] op_sel_hi:[0,1]
	v_lshlrev_b64 v[16:17], 11, v[16:17]
	v_pk_fma_f32 v[36:37], v[4:5], v[36:37], v[86:87]
	v_pk_fma_f32 v[38:39], v[6:7], v[38:39], v[80:81]
	v_pk_fma_f32 v[34:35], v[8:9], v[34:35], v[94:95]
	v_pk_fma_f32 v[26:27], v[10:11], v[26:27], v[88:89]
	v_pk_fma_f32 v[30:31], v[12:13], v[30:31], v[102:103]
	v_pk_fma_f32 v[18:19], v[14:15], v[18:19], v[96:97]
	v_lshl_add_u64 v[16:17], v[32:33], 0, v[16:17]
	v_cvt_pk_bf16_f32 v20, v20, v21
	v_cvt_pk_bf16_f32 v21, v24, v25
	global_store_dwordx2 v[16:17], v[20:21], off
	v_cvt_pk_bf16_f32 v20, v36, v37
	v_cvt_pk_bf16_f32 v21, v38, v39
	v_cvt_pk_bf16_f32 v34, v34, v35
	v_cvt_pk_bf16_f32 v35, v26, v27
	v_cvt_pk_bf16_f32 v30, v30, v31
	v_cvt_pk_bf16_f32 v31, v18, v19
	global_store_dwordx2 v[16:17], v[20:21], off offset:512
	global_store_dwordx2 v[16:17], v[34:35], off offset:1024
	global_store_dwordx2 v[16:17], v[30:31], off offset:1536
	v_subrev_u32_e32 v16, s70, v104
	v_cmp_lt_i32_e32 vcc, v125, v16
	s_or_b64 s[4:5], vcc, s[4:5]
	s_andn2_b64 exec, exec, s[4:5]
	s_cbranch_execz .LBB0_96
.Lrp95_top2:
	v_add_u32_e32 v104, s71, v16
	v_cmp_gt_i32_e32 vcc, v124, v104
	s_nop 1
	v_cndmask_b32_e32 v38, v16, v104, vcc
	v_ashrrev_i32_e32 v39, 31, v38
	v_lshlrev_b64 v[38:39], 11, v[38:39]
	v_lshl_add_u64 v[30:31], v[22:23], 0, v[38:39]
	v_lshl_add_u64 v[18:19], v[28:29], 0, v[38:39]
	global_load_dwordx2 v[38:39], v[30:31], off
	global_load_dwordx2 v[36:37], v[30:31], off offset:512
	global_load_dwordx2 v[34:35], v[30:31], off offset:1024
	s_nop 0
	global_load_dwordx2 v[30:31], v[30:31], off offset:1536
	s_nop 0
	global_load_dwordx2 v[26:27], v[18:19], off
	global_load_dwordx2 v[24:25], v[18:19], off offset:512
	global_load_dwordx2 v[20:21], v[18:19], off offset:1024
	s_nop 0
	global_load_dwordx2 v[18:19], v[18:19], off offset:1536
	v_and_b32_e32 v17, 64, v207
	v_add_u32_e32 v17, 64, v17
	v_xor_b32_e32 v72, 32, v207
	v_cmp_lt_i32_e32 vcc, v72, v17
	s_waitcnt vmcnt(24)
	v_and_b32_e32 v73, 0xffff0000, v57
	v_lshlrev_b32_e32 v78, 16, v56
	v_cndmask_b32_e32 v72, v207, v72, vcc
	v_lshlrev_b32_e32 v105, 2, v72
	v_xor_b32_e32 v72, 16, v207
	v_cmp_lt_i32_e32 vcc, v72, v17
	v_and_b32_e32 v79, 0xffff0000, v56
	v_lshlrev_b32_e32 v56, 16, v64
	v_cndmask_b32_e32 v72, v207, v72, vcc
	v_lshlrev_b32_e32 v106, 2, v72
	v_xor_b32_e32 v72, 8, v207
	v_cmp_lt_i32_e32 vcc, v72, v17
	v_lshlrev_b32_e32 v74, 16, v65
	v_and_b32_e32 v75, 0xffff0000, v65
	v_cndmask_b32_e32 v72, v207, v72, vcc
	v_lshlrev_b32_e32 v107, 2, v72
	v_xor_b32_e32 v72, 4, v207
	v_cmp_lt_i32_e32 vcc, v72, v17
	v_pk_mul_f32 v[76:77], v[74:75], v[74:75]
	v_lshlrev_b32_e32 v80, 16, v59
	v_cndmask_b32_e32 v72, v207, v72, vcc
	v_lshlrev_b32_e32 v108, 2, v72
	v_xor_b32_e32 v72, 2, v207
	v_cmp_lt_i32_e32 vcc, v72, v17
	s_waitcnt lgkmcnt(0)
	v_and_b32_e32 v81, 0xffff0000, v59
	v_lshlrev_b32_e32 v86, 16, v58
	v_cndmask_b32_e32 v72, v207, v72, vcc
	v_lshlrev_b32_e32 v109, 2, v72
	v_xor_b32_e32 v72, 1, v207
	v_cmp_lt_i32_e32 vcc, v72, v17
	v_and_b32_e32 v87, 0xffff0000, v58
	v_lshlrev_b32_e32 v58, 16, v66
	v_cndmask_b32_e32 v17, v207, v72, vcc
	v_lshlrev_b32_e32 v72, 16, v57
	v_and_b32_e32 v57, 0xffff0000, v64
	v_pk_mul_f32 v[64:65], v[56:57], v[56:57]
	v_and_b32_e32 v59, 0xffff0000, v66
	v_add_f32_e32 v64, v64, v65
	v_add_f32_e32 v64, v76, v64
	v_lshlrev_b32_e32 v82, 16, v67
	v_and_b32_e32 v83, 0xffff0000, v67
	v_pk_mul_f32 v[66:67], v[58:59], v[58:59]
	v_add_f32_e32 v64, v77, v64
	v_add_f32_e32 v66, v66, v64
	v_pk_mul_f32 v[84:85], v[82:83], v[82:83]
	v_add_f32_e32 v66, v67, v66
	v_lshlrev_b32_e32 v88, 16, v61
	v_and_b32_e32 v89, 0xffff0000, v61
	v_lshlrev_b32_e32 v94, 16, v60
	v_and_b32_e32 v95, 0xffff0000, v60
	v_lshlrev_b32_e32 v60, 16, v68
	v_and_b32_e32 v61, 0xffff0000, v68
	v_add_f32_e32 v66, v84, v66
	v_lshlrev_b32_e32 v90, 16, v69
	v_and_b32_e32 v91, 0xffff0000, v69
	v_pk_mul_f32 v[68:69], v[60:61], v[60:61]
	v_add_f32_e32 v66, v85, v66
	v_add_f32_e32 v68, v68, v66
	v_pk_mul_f32 v[92:93], v[90:91], v[90:91]
	v_add_f32_e32 v68, v69, v68
	v_lshlrev_b32_e32 v96, 16, v63
	v_and_b32_e32 v97, 0xffff0000, v63
	v_lshlrev_b32_e32 v102, 16, v62
	v_and_b32_e32 v103, 0xffff0000, v62
	v_lshlrev_b32_e32 v62, 16, v70
	v_and_b32_e32 v63, 0xffff0000, v70
	v_add_f32_e32 v68, v92, v68
	v_lshlrev_b32_e32 v98, 16, v71
	v_and_b32_e32 v99, 0xffff0000, v71
	v_pk_mul_f32 v[70:71], v[62:63], v[62:63]
	v_add_f32_e32 v68, v93, v68
	v_add_f32_e32 v70, v70, v68
	v_pk_mul_f32 v[100:101], v[98:99], v[98:99]
	v_add_f32_e32 v70, v71, v70
	v_add_f32_e32 v70, v100, v70
	v_add_f32_e32 v70, v101, v70
	ds_bpermute_b32 v71, v105, v70
	v_lshlrev_b32_e32 v17, 2, v17
	s_waitcnt lgkmcnt(0)
	v_add_f32_e32 v70, v70, v71
	ds_bpermute_b32 v71, v106, v70
	s_waitcnt lgkmcnt(0)
	v_add_f32_e32 v70, v70, v71
	ds_bpermute_b32 v71, v107, v70
	s_waitcnt lgkmcnt(0)
	v_add_f32_e32 v70, v70, v71
	ds_bpermute_b32 v71, v108, v70
	s_waitcnt lgkmcnt(0)
	v_add_f32_e32 v70, v70, v71
	ds_bpermute_b32 v71, v109, v70
	s_waitcnt lgkmcnt(0)
	v_add_f32_e32 v70, v70, v71
	ds_bpermute_b32 v17, v17, v70
	s_waitcnt lgkmcnt(0)
	v_add_f32_e32 v17, v70, v17
	v_fmamk_f32 v17, v17, 0x3a800000, v205
	v_cmp_gt_f32_e32 vcc, s30, v17
	v_mul_f32_e32 v70, 0x4b800000, v17
	s_nop 0
	v_cndmask_b32_e32 v17, v17, v70, vcc
	v_rsq_f32_e32 v17, v17
	s_nop 0
	v_mul_f32_e32 v70, 0x45800000, v17
	v_cndmask_b32_e32 v70, v17, v70, vcc
	v_pk_mul_f32 v[68:69], v[70:71], v[56:57] op_sel_hi:[0,1]
	v_pk_mul_f32 v[66:67], v[70:71], v[74:75] op_sel_hi:[0,1]
	v_ashrrev_i32_e32 v17, 31, v16
	v_pk_fma_f32 v[68:69], v[0:1], v[68:69], v[78:79]
	v_pk_fma_f32 v[66:67], v[2:3], v[66:67], v[72:73]
	v_pk_mul_f32 v[58:59], v[70:71], v[58:59] op_sel_hi:[0,1]
	v_pk_mul_f32 v[56:57], v[70:71], v[82:83] op_sel_hi:[0,1]
	v_pk_mul_f32 v[60:61], v[70:71], v[60:61] op_sel_hi:[0,1]
	v_pk_mul_f32 v[64:65], v[70:71], v[90:91] op_sel_hi:[0,1]
	v_pk_mul_f32 v[62:63], v[70:71], v[62:63] op_sel_hi:[0,1]
	v_pk_mul_f32 v[70:71], v[70:71], v[98:99] op_sel_hi:[0,1]
	v_lshlrev_b64 v[16:17], 11, v[16:17]
	v_pk_fma_f32 v[58:59], v[4:5], v[58:59], v[86:87]
	v_pk_fma_f32 v[56:57], v[6:7], v[56:57], v[80:81]
	v_pk_fma_f32 v[60:61], v[8:9], v[60:61], v[94:95]
	v_pk_fma_f32 v[64:65], v[10:11], v[64:65], v[88:89]
	v_pk_fma_f32 v[62:63], v[12:13], v[62:63], v[102:103]
	v_pk_fma_f32 v[70:71], v[14:15], v[70:71], v[96:97]
	v_lshl_add_u64 v[16:17], v[32:33], 0, v[16:17]
	v_cvt_pk_bf16_f32 v68, v68, v69
	v_cvt_pk_bf16_f32 v69, v66, v67
	global_store_dwordx2 v[16:17], v[68:69], off
	v_cvt_pk_bf16_f32 v68, v58, v59
	v_cvt_pk_bf16_f32 v69, v56, v57
	v_cvt_pk_bf16_f32 v60, v60, v61
	v_cvt_pk_bf16_f32 v61, v64, v65
	v_cvt_pk_bf16_f32 v62, v62, v63
	v_cvt_pk_bf16_f32 v63, v70, v71
	global_store_dwordx2 v[16:17], v[68:69], off offset:512
	global_store_dwordx2 v[16:17], v[60:61], off offset:1024
	global_store_dwordx2 v[16:17], v[62:63], off offset:1536
	v_subrev_u32_e32 v16, s70, v104
	v_cmp_lt_i32_e32 vcc, v125, v16
	s_or_b64 s[4:5], vcc, s[4:5]
	s_andn2_b64 exec, exec, s[4:5]
	s_cbranch_execnz .LBB0_95

.LBB0_130:
	v_readlane_b32 s0, v255, 23
	s_cmp_lt_i32 s0, 8
	s_mov_b64 s[2:3], -1
	s_cbranch_scc1 .LBB0_156
	v_readlane_b32 s0, v255, 23
	s_cmp_gt_i32 s0, 8
	s_cbranch_scc0 .LBB0_142
	v_mov_b32_e32 v0, v204
	s_nop 0
	v_ashrrev_i32_e32 v0, 6, v0
	v_add_u32_e32 v32, s69, v0
	s_cmp_eq_u32 s70, 1
	s_cbranch_scc0 .Lrm1_old
	v_lshlrev_b32_e32 v32, 4, v32
	v_add_u32_e32 v124, 16, v32
	s_branch .Lrm1_done

.Lrm1_done:
	v_add_u32_e32 v125, -1, v124
	v_mov_b32_e32 v0, v204
	v_cmp_gt_i32_e32 vcc, v124, v32
	s_and_saveexec_b64 s[2:3], vcc
	s_cbranch_execz .LBB0_141
	v_ashrrev_i32_e32 v33, 31, v32
	v_readlane_b32 s10, v253, 2
	v_lshlrev_b64 v[2:3], 11, v[32:33]
	v_readlane_b32 s11, v253, 3
	v_lshlrev_b32_e32 v0, 2, v0
	v_and_b32_e32 v6, 0xfc, v0
	v_lshl_add_u64 v[4:5], s[10:11], 0, v[2:3]
	v_readlane_b32 s10, v252, 62
	v_readlane_b32 s4, v255, 21
	v_lshlrev_b32_e32 v188, 1, v6
	v_readlane_b32 s11, v252, 63
	v_readlane_b32 s5, v255, 22
	s_lshl_b32 s4, s4, 10
	v_lshl_add_u64 v[0:1], v[4:5], 0, v[188:189]
	v_lshl_add_u64 v[2:3], s[10:11], 0, v[2:3]
	s_ashr_i32 s5, s4, 31
	v_readlane_b32 s12, v252, 28
	v_lshl_add_u64 v[2:3], v[2:3], 0, v[188:189]
	global_load_dwordx2 v[50:51], v[0:1], off
	global_load_dwordx2 v[40:41], v[0:1], off offset:512
	global_load_dwordx2 v[34:35], v[0:1], off offset:1024
	global_load_dwordx2 v[36:37], v[0:1], off offset:1536
	global_load_dwordx2 v[86:87], v[2:3], off
	global_load_dwordx2 v[84:85], v[2:3], off offset:512
	global_load_dwordx2 v[82:83], v[2:3], off offset:1024
	global_load_dwordx2 v[64:65], v[2:3], off offset:1536
	s_lshl_b64 s[8:9], s[4:5], 2
	v_readlane_b32 s18, v252, 34
	v_readlane_b32 s19, v252, 35
	s_add_u32 s4, s18, s8
	s_addc_u32 s5, s19, s9
	v_lshlrev_b32_e32 v28, 2, v6
	global_load_dwordx4 v[0:3], v28, s[4:5]
	global_load_dwordx4 v[4:7], v28, s[4:5] offset:1024
	global_load_dwordx4 v[8:11], v28, s[4:5] offset:2048
	global_load_dwordx4 v[12:15], v28, s[4:5] offset:3072
	v_readlane_b32 s10, v253, 27
	v_readlane_b32 s11, v253, 28
	v_readlane_b32 s20, v252, 36
	v_readlane_b32 s21, v252, 37
	v_cndmask_b32_e64 v16, 0, 1, s[10:11]
	v_cmp_ne_u32_e64 s[4:5], 1, v16
	s_andn2_b64 vcc, exec, s[10:11]
	v_readlane_b32 s13, v252, 29
	v_readlane_b32 s14, v252, 30
	v_readlane_b32 s15, v252, 31
	v_readlane_b32 s16, v252, 32
	v_readlane_b32 s17, v252, 33
	v_readlane_b32 s22, v252, 38
	v_readlane_b32 s23, v252, 39
	v_readlane_b32 s24, v252, 40
	v_readlane_b32 s25, v252, 41
	v_readlane_b32 s26, v252, 42
	v_readlane_b32 s27, v252, 43
	s_cbranch_vccnz .LBB0_135
	s_add_u32 s8, s20, s8
	s_addc_u32 s9, s21, s9
	global_load_dwordx4 v[16:19], v28, s[8:9]
	global_load_dwordx4 v[20:23], v28, s[8:9] offset:1024
	global_load_dwordx4 v[24:27], v28, s[8:9] offset:2048
	s_nop 0
	global_load_dwordx4 v[28:31], v28, s[8:9] offset:3072
	s_branch .LBB0_136

.LBB0_136:
	v_add_u32_e32 v33, s70, v32
	v_cmp_gt_i32_e32 vcc, v124, v33
	v_readlane_b32 s8, v252, 62
	v_readlane_b32 s10, v253, 2
	v_cndmask_b32_e32 v38, v32, v33, vcc
	v_ashrrev_i32_e32 v39, 31, v38
	v_lshlrev_b64 v[48:49], 11, v[38:39]
	v_readlane_b32 s9, v252, 63
	v_readlane_b32 s11, v253, 3
	s_nop 0
	v_lshl_add_u64 v[38:39], s[8:9], 0, v[48:49]
	v_lshl_add_u64 v[48:49], s[10:11], 0, v[48:49]
	v_lshl_add_u64 v[46:47], v[38:39], 0, v[188:189]
	v_lshl_add_u64 v[48:49], v[48:49], 0, v[188:189]
	global_load_dwordx2 v[38:39], v[46:47], off offset:1536
	global_load_dwordx2 v[42:43], v[46:47], off offset:1024
	global_load_dwordx2 v[44:45], v[46:47], off offset:512
	s_nop 0
	global_load_dwordx2 v[46:47], v[46:47], off
	s_nop 0
	global_load_dwordx2 v[54:55], v[48:49], off offset:1536
	global_load_dwordx2 v[56:57], v[48:49], off offset:1024
	global_load_dwordx2 v[60:61], v[48:49], off offset:512
	global_load_dwordx2 v[62:63], v[48:49], off
	v_lshl_add_u64 v[52:53], s[8:9], 0, v[188:189]
	v_readlane_b32 s8, v254, 32
	v_readlane_b32 s9, v254, 33
	v_lshl_add_u64 v[48:49], s[10:11], 0, v[188:189]
	s_nop 0
	v_lshl_add_u64 v[58:59], s[8:9], 0, v[188:189]
	s_mov_b64 s[8:9], 0
	s_waitcnt vmcnt(0)
	s_branch .LBB0_139
.LBB0_139:
	v_add_u32_e32 v89, s71, v32
	v_cmp_gt_i32_e32 vcc, v124, v89
	s_nop 1
	v_cndmask_b32_e32 v66, v32, v89, vcc
	v_ashrrev_i32_e32 v67, 31, v66
	v_lshlrev_b64 v[66:67], 11, v[66:67]
	v_lshl_add_u64 v[72:73], v[48:49], 0, v[66:67]
	s_waitcnt lgkmcnt(0)
	v_lshl_add_u64 v[80:81], v[52:53], 0, v[66:67]
	global_load_dwordx2 v[66:67], v[72:73], off
	global_load_dwordx2 v[68:69], v[72:73], off offset:512
	global_load_dwordx2 v[70:71], v[72:73], off offset:1024
	s_nop 0
	global_load_dwordx2 v[72:73], v[72:73], off offset:1536
	s_nop 0
	global_load_dwordx2 v[74:75], v[80:81], off
	global_load_dwordx2 v[76:77], v[80:81], off offset:512
	global_load_dwordx2 v[78:79], v[80:81], off offset:1024
	s_nop 0
	global_load_dwordx2 v[80:81], v[80:81], off offset:1536
	s_waitcnt vmcnt(32)
	v_lshlrev_b32_e32 v100, 16, v86
	v_and_b32_e32 v101, 0xffff0000, v86
	v_lshlrev_b32_e32 v96, 16, v87
	v_and_b32_e32 v97, 0xffff0000, v87
	v_pk_mul_f32 v[86:87], v[100:101], v[100:101]
	v_pk_mul_f32 v[98:99], v[96:97], v[96:97]
	v_add_f32_e32 v86, v86, v87
	v_lshlrev_b32_e32 v106, 16, v84
	v_and_b32_e32 v107, 0xffff0000, v84
	v_add_f32_e32 v86, v98, v86
	v_lshlrev_b32_e32 v102, 16, v85
	v_and_b32_e32 v103, 0xffff0000, v85
	v_pk_mul_f32 v[84:85], v[106:107], v[106:107]
	v_add_f32_e32 v86, v99, v86
	v_add_f32_e32 v84, v84, v86
	v_pk_mul_f32 v[104:105], v[102:103], v[102:103]
	v_add_f32_e32 v84, v85, v84
	v_lshlrev_b32_e32 v112, 16, v82
	v_and_b32_e32 v113, 0xffff0000, v82
	v_add_f32_e32 v84, v104, v84
	v_lshlrev_b32_e32 v108, 16, v83
	v_and_b32_e32 v109, 0xffff0000, v83
	v_pk_mul_f32 v[82:83], v[112:113], v[112:113]
	v_add_f32_e32 v84, v105, v84
	v_add_f32_e32 v82, v82, v84
	v_pk_mul_f32 v[110:111], v[108:109], v[108:109]
	v_add_f32_e32 v82, v83, v82
	v_lshlrev_b32_e32 v114, 16, v64
	v_and_b32_e32 v115, 0xffff0000, v64
	v_add_f32_e32 v82, v110, v82
	v_and_b32_e32 v33, 64, v207
	v_and_b32_e32 v95, 0xffff0000, v65
	v_lshlrev_b32_e32 v94, 16, v65
	v_pk_mul_f32 v[64:65], v[114:115], v[114:115]
	v_add_f32_e32 v82, v111, v82
	v_add_u32_e32 v116, 64, v33
	v_xor_b32_e32 v33, 32, v207
	v_add_f32_e32 v64, v64, v82
	v_cmp_lt_i32_e32 vcc, v33, v116
	v_pk_mul_f32 v[92:93], v[94:95], v[94:95]
	v_add_f32_e32 v64, v65, v64
	v_cndmask_b32_e32 v33, v207, v33, vcc
	v_add_f32_e32 v64, v92, v64
	v_lshlrev_b32_e32 v33, 2, v33
	v_add_f32_e32 v64, v93, v64
	ds_bpermute_b32 v65, v33, v64
	v_xor_b32_e32 v88, 16, v207
	v_cmp_lt_i32_e32 vcc, v88, v116
	v_xor_b32_e32 v90, 8, v207
	v_xor_b32_e32 v91, 4, v207
	v_cndmask_b32_e32 v88, v207, v88, vcc
	v_lshlrev_b32_e32 v88, 2, v88
	s_waitcnt lgkmcnt(0)
	v_add_f32_e32 v64, v64, v65
	ds_bpermute_b32 v65, v88, v64
	v_cmp_lt_i32_e32 vcc, v90, v116
	v_and_b32_e32 v99, 0xffff0000, v37
	v_lshlrev_b32_e32 v98, 16, v37
	v_cndmask_b32_e32 v90, v207, v90, vcc
	v_lshlrev_b32_e32 v90, 2, v90
	s_waitcnt lgkmcnt(0)
	v_add_f32_e32 v64, v64, v65
	ds_bpermute_b32 v65, v90, v64
	v_cmp_lt_i32_e32 vcc, v91, v116
	v_lshlrev_b32_e32 v104, 16, v40
	v_and_b32_e32 v105, 0xffff0000, v40
	v_cndmask_b32_e32 v82, v207, v91, vcc
	v_lshlrev_b32_e32 v91, 2, v82
	s_waitcnt lgkmcnt(0)
	v_add_f32_e32 v83, v64, v65
	ds_bpermute_b32 v84, v91, v83
	v_xor_b32_e32 v82, 2, v207
	v_cmp_lt_i32_e32 vcc, v82, v116
	v_lshlrev_b32_e32 v64, 16, v51
	v_and_b32_e32 v65, 0xffff0000, v51
	v_cndmask_b32_e32 v82, v207, v82, vcc
	v_lshlrev_b32_e32 v92, 2, v82
	s_waitcnt lgkmcnt(0)
	v_add_f32_e32 v37, v83, v84
	ds_bpermute_b32 v84, v92, v37
	v_xor_b32_e32 v82, 1, v207
	v_cmp_lt_i32_e32 vcc, v82, v116
	v_and_b32_e32 v83, 0xffff0000, v50
	v_and_b32_e32 v51, 0xffff0000, v41
	v_cndmask_b32_e32 v82, v207, v82, vcc
	v_lshlrev_b32_e32 v93, 2, v82
	s_waitcnt lgkmcnt(0)
	v_add_f32_e32 v37, v37, v84
	ds_bpermute_b32 v84, v93, v37
	v_lshlrev_b32_e32 v82, 16, v50
	v_lshlrev_b32_e32 v50, 16, v41
	v_lshlrev_b32_e32 v40, 16, v35
	v_and_b32_e32 v41, 0xffff0000, v35
	s_waitcnt lgkmcnt(0)
	v_add_f32_e32 v35, v37, v84
	v_fmamk_f32 v35, v35, 0x3a800000, v205
	v_mul_f32_e32 v37, 0x4b800000, v35
	v_cmp_gt_f32_e32 vcc, s30, v35
	v_lshlrev_b32_e32 v110, 16, v34
	v_and_b32_e32 v111, 0xffff0000, v34
	v_cndmask_b32_e32 v35, v35, v37, vcc
	v_rsq_f32_e32 v37, v35
	v_lshlrev_b32_e32 v34, 16, v36
	v_and_b32_e32 v35, 0xffff0000, v36
	v_mul_f32_e32 v36, 0x45800000, v37
	v_cndmask_b32_e32 v36, v37, v36, vcc
	v_pk_mul_f32 v[84:85], v[36:37], v[100:101] op_sel_hi:[0,1]
	v_pk_fma_f32 v[86:87], v[0:1], v[84:85], v[82:83]
	v_pk_mul_f32 v[82:83], v[36:37], v[96:97] op_sel_hi:[0,1]
	v_pk_fma_f32 v[84:85], v[2:3], v[82:83], v[64:65]
	v_pk_mul_f32 v[64:65], v[36:37], v[106:107] op_sel_hi:[0,1]
	v_pk_fma_f32 v[82:83], v[4:5], v[64:65], v[104:105]
	v_pk_mul_f32 v[64:65], v[36:37], v[102:103] op_sel_hi:[0,1]
	v_pk_mul_f32 v[96:97], v[36:37], v[108:109] op_sel_hi:[0,1]
	v_pk_fma_f32 v[64:65], v[6:7], v[64:65], v[50:51]
	v_pk_mul_f32 v[50:51], v[36:37], v[112:113] op_sel_hi:[0,1]
	v_pk_fma_f32 v[40:41], v[10:11], v[96:97], v[40:41]
	v_pk_mul_f32 v[96:97], v[36:37], v[114:115] op_sel_hi:[0,1]
	v_pk_mul_f32 v[36:37], v[36:37], v[94:95] op_sel_hi:[0,1]
	v_pk_fma_f32 v[50:51], v[8:9], v[50:51], v[110:111]
	v_pk_fma_f32 v[34:35], v[12:13], v[96:97], v[34:35]
	s_and_b64 vcc, exec, s[4:5]
	v_pk_fma_f32 v[36:37], v[14:15], v[36:37], v[98:99]
	s_cbranch_vccz .Lrp139_n2_0
	v_mov_b32_e32 v88, 1.0
	s_branch .Lrp139_st_0

.Lrp139_st_0:
	v_ashrrev_i32_e32 v33, 31, v32
	v_lshlrev_b64 v[32:33], 11, v[32:33]
	v_lshl_add_u64 v[90:91], v[48:49], 0, v[32:33]
	v_cvt_pk_bf16_f32 v92, v86, v87
	v_cvt_pk_bf16_f32 v93, v84, v85
	global_store_dwordx2 v[90:91], v[92:93], off
	v_cvt_pk_bf16_f32 v92, v82, v83
	v_cvt_pk_bf16_f32 v93, v64, v65
	global_store_dwordx2 v[90:91], v[92:93], off offset:512
	v_cvt_pk_bf16_f32 v92, v50, v51
	v_cvt_pk_bf16_f32 v93, v40, v41
	global_store_dwordx2 v[90:91], v[92:93], off offset:1024
	v_cvt_pk_bf16_f32 v92, v34, v35
	v_cvt_pk_bf16_f32 v93, v36, v37
	v_pk_mul_f32 v[86:87], v[86:87], v[88:89] op_sel_hi:[1,0]
	v_pk_mul_f32 v[84:85], v[84:85], v[88:89] op_sel_hi:[1,0]
	v_pk_mul_f32 v[82:83], v[82:83], v[88:89] op_sel_hi:[1,0]
	v_pk_mul_f32 v[64:65], v[64:65], v[88:89] op_sel_hi:[1,0]
	v_pk_mul_f32 v[50:51], v[50:51], v[88:89] op_sel_hi:[1,0]
	v_pk_mul_f32 v[40:41], v[40:41], v[88:89] op_sel_hi:[1,0]
	v_pk_mul_f32 v[34:35], v[34:35], v[88:89] op_sel_hi:[1,0]
	v_pk_mul_f32 v[36:37], v[36:37], v[88:89] op_sel_hi:[1,0]
	v_pk_mul_f32 v[86:87], v[16:17], v[86:87]
	v_pk_mul_f32 v[84:85], v[18:19], v[84:85]
	v_pk_mul_f32 v[82:83], v[20:21], v[82:83]
	v_pk_mul_f32 v[64:65], v[22:23], v[64:65]
	v_pk_mul_f32 v[50:51], v[24:25], v[50:51]
	v_pk_mul_f32 v[40:41], v[26:27], v[40:41]
	v_pk_mul_f32 v[34:35], v[28:29], v[34:35]
	v_pk_mul_f32 v[36:37], v[30:31], v[36:37]
	v_lshl_add_u64 v[32:33], v[58:59], 0, v[32:33]
	v_cvt_pk_bf16_f32 v86, v86, v87
	v_cvt_pk_bf16_f32 v87, v84, v85
	v_cvt_pk_bf16_f32 v82, v82, v83
	v_cvt_pk_bf16_f32 v83, v64, v65
	v_cvt_pk_bf16_f32 v50, v50, v51
	v_cvt_pk_bf16_f32 v51, v40, v41
	v_cvt_pk_bf16_f32 v34, v34, v35
	v_cvt_pk_bf16_f32 v35, v36, v37
	global_store_dwordx2 v[90:91], v[92:93], off offset:1536
	global_store_dwordx2 v[32:33], v[86:87], off
	global_store_dwordx2 v[32:33], v[82:83], off offset:512
	global_store_dwordx2 v[32:33], v[50:51], off offset:1024
	global_store_dwordx2 v[32:33], v[34:35], off offset:1536
	v_subrev_u32_e32 v32, s70, v89
	v_cmp_lt_i32_e32 vcc, v125, v32
	s_or_b64 s[8:9], vcc, s[8:9]
	s_andn2_b64 exec, exec, s[8:9]
	s_cbranch_execz .LBB0_141
.Lrp139_top1:
	v_add_u32_e32 v89, s71, v32
	v_cmp_gt_i32_e32 vcc, v124, v89
	s_nop 1
	v_cndmask_b32_e32 v50, v32, v89, vcc
	v_ashrrev_i32_e32 v51, 31, v50
	v_lshlrev_b64 v[50:51], 11, v[50:51]
	v_lshl_add_u64 v[36:37], v[48:49], 0, v[50:51]
	s_waitcnt lgkmcnt(0)
	v_lshl_add_u64 v[64:65], v[52:53], 0, v[50:51]
	global_load_dwordx2 v[50:51], v[36:37], off
	global_load_dwordx2 v[40:41], v[36:37], off offset:512
	global_load_dwordx2 v[34:35], v[36:37], off offset:1024
	s_nop 0
	global_load_dwordx2 v[36:37], v[36:37], off offset:1536
	s_nop 0
	global_load_dwordx2 v[86:87], v[64:65], off
	global_load_dwordx2 v[84:85], v[64:65], off offset:512
	global_load_dwordx2 v[82:83], v[64:65], off offset:1024
	s_nop 0
	global_load_dwordx2 v[64:65], v[64:65], off offset:1536
	s_waitcnt vmcnt(32)
	v_lshlrev_b32_e32 v100, 16, v46
	v_and_b32_e32 v101, 0xffff0000, v46
	v_lshlrev_b32_e32 v96, 16, v47
	v_and_b32_e32 v97, 0xffff0000, v47
	v_pk_mul_f32 v[46:47], v[100:101], v[100:101]
	v_pk_mul_f32 v[98:99], v[96:97], v[96:97]
	v_add_f32_e32 v46, v46, v47
	v_lshlrev_b32_e32 v106, 16, v44
	v_and_b32_e32 v107, 0xffff0000, v44
	v_add_f32_e32 v46, v98, v46
	v_lshlrev_b32_e32 v102, 16, v45
	v_and_b32_e32 v103, 0xffff0000, v45
	v_pk_mul_f32 v[44:45], v[106:107], v[106:107]
	v_add_f32_e32 v46, v99, v46
	v_add_f32_e32 v44, v44, v46
	v_pk_mul_f32 v[104:105], v[102:103], v[102:103]
	v_add_f32_e32 v44, v45, v44
	v_lshlrev_b32_e32 v112, 16, v42
	v_and_b32_e32 v113, 0xffff0000, v42
	v_add_f32_e32 v44, v104, v44
	v_lshlrev_b32_e32 v108, 16, v43
	v_and_b32_e32 v109, 0xffff0000, v43
	v_pk_mul_f32 v[42:43], v[112:113], v[112:113]
	v_add_f32_e32 v44, v105, v44
	v_add_f32_e32 v42, v42, v44
	v_pk_mul_f32 v[110:111], v[108:109], v[108:109]
	v_add_f32_e32 v42, v43, v42
	v_lshlrev_b32_e32 v114, 16, v38
	v_and_b32_e32 v115, 0xffff0000, v38
	v_add_f32_e32 v42, v110, v42
	v_and_b32_e32 v33, 64, v207
	v_and_b32_e32 v95, 0xffff0000, v39
	v_lshlrev_b32_e32 v94, 16, v39
	v_pk_mul_f32 v[38:39], v[114:115], v[114:115]
	v_add_f32_e32 v42, v111, v42
	v_add_u32_e32 v116, 64, v33
	v_xor_b32_e32 v33, 32, v207
	v_add_f32_e32 v38, v38, v42
	v_cmp_lt_i32_e32 vcc, v33, v116
	v_pk_mul_f32 v[92:93], v[94:95], v[94:95]
	v_add_f32_e32 v38, v39, v38
	v_cndmask_b32_e32 v33, v207, v33, vcc
	v_add_f32_e32 v38, v92, v38
	v_lshlrev_b32_e32 v33, 2, v33
	v_add_f32_e32 v38, v93, v38
	ds_bpermute_b32 v39, v33, v38
	v_xor_b32_e32 v88, 16, v207
	v_cmp_lt_i32_e32 vcc, v88, v116
	v_xor_b32_e32 v90, 8, v207
	v_xor_b32_e32 v91, 4, v207
	v_cndmask_b32_e32 v88, v207, v88, vcc
	v_lshlrev_b32_e32 v88, 2, v88
	s_waitcnt lgkmcnt(0)
	v_add_f32_e32 v38, v38, v39
	ds_bpermute_b32 v39, v88, v38
	v_cmp_lt_i32_e32 vcc, v90, v116
	v_and_b32_e32 v99, 0xffff0000, v55
	v_lshlrev_b32_e32 v98, 16, v55
	v_cndmask_b32_e32 v90, v207, v90, vcc
	v_lshlrev_b32_e32 v90, 2, v90
	s_waitcnt lgkmcnt(0)
	v_add_f32_e32 v38, v38, v39
	ds_bpermute_b32 v39, v90, v38
	v_cmp_lt_i32_e32 vcc, v91, v116
	v_lshlrev_b32_e32 v104, 16, v60
	v_and_b32_e32 v105, 0xffff0000, v60
	v_cndmask_b32_e32 v42, v207, v91, vcc
	v_lshlrev_b32_e32 v91, 2, v42
	s_waitcnt lgkmcnt(0)
	v_add_f32_e32 v43, v38, v39
	ds_bpermute_b32 v44, v91, v43
	v_xor_b32_e32 v42, 2, v207
	v_cmp_lt_i32_e32 vcc, v42, v116
	v_lshlrev_b32_e32 v38, 16, v63
	v_and_b32_e32 v39, 0xffff0000, v63
	v_cndmask_b32_e32 v42, v207, v42, vcc
	v_lshlrev_b32_e32 v92, 2, v42
	s_waitcnt lgkmcnt(0)
	v_add_f32_e32 v55, v43, v44
	ds_bpermute_b32 v44, v92, v55
	v_xor_b32_e32 v42, 1, v207
	v_cmp_lt_i32_e32 vcc, v42, v116
	v_and_b32_e32 v43, 0xffff0000, v62
	v_and_b32_e32 v63, 0xffff0000, v61
	v_cndmask_b32_e32 v42, v207, v42, vcc
	v_lshlrev_b32_e32 v93, 2, v42
	s_waitcnt lgkmcnt(0)
	v_add_f32_e32 v55, v55, v44
	ds_bpermute_b32 v44, v93, v55
	v_lshlrev_b32_e32 v42, 16, v62
	v_lshlrev_b32_e32 v62, 16, v61
	v_lshlrev_b32_e32 v60, 16, v57
	v_and_b32_e32 v61, 0xffff0000, v57
	s_waitcnt lgkmcnt(0)
	v_add_f32_e32 v57, v55, v44
	v_fmamk_f32 v57, v57, 0x3a800000, v205
	v_mul_f32_e32 v55, 0x4b800000, v57
	v_cmp_gt_f32_e32 vcc, s30, v57
	v_lshlrev_b32_e32 v110, 16, v56
	v_and_b32_e32 v111, 0xffff0000, v56
	v_cndmask_b32_e32 v57, v57, v55, vcc
	v_rsq_f32_e32 v55, v57
	v_lshlrev_b32_e32 v56, 16, v54
	v_and_b32_e32 v57, 0xffff0000, v54
	v_mul_f32_e32 v54, 0x45800000, v55
	v_cndmask_b32_e32 v54, v55, v54, vcc
	v_pk_mul_f32 v[44:45], v[54:55], v[100:101] op_sel_hi:[0,1]
	v_pk_fma_f32 v[46:47], v[0:1], v[44:45], v[42:43]
	v_pk_mul_f32 v[42:43], v[54:55], v[96:97] op_sel_hi:[0,1]
	v_pk_fma_f32 v[44:45], v[2:3], v[42:43], v[38:39]
	v_pk_mul_f32 v[38:39], v[54:55], v[106:107] op_sel_hi:[0,1]
	v_pk_fma_f32 v[42:43], v[4:5], v[38:39], v[104:105]
	v_pk_mul_f32 v[38:39], v[54:55], v[102:103] op_sel_hi:[0,1]
	v_pk_mul_f32 v[96:97], v[54:55], v[108:109] op_sel_hi:[0,1]
	v_pk_fma_f32 v[38:39], v[6:7], v[38:39], v[62:63]
	v_pk_mul_f32 v[62:63], v[54:55], v[112:113] op_sel_hi:[0,1]
	v_pk_fma_f32 v[60:61], v[10:11], v[96:97], v[60:61]
	v_pk_mul_f32 v[96:97], v[54:55], v[114:115] op_sel_hi:[0,1]
	v_pk_mul_f32 v[54:55], v[54:55], v[94:95] op_sel_hi:[0,1]
	v_pk_fma_f32 v[62:63], v[8:9], v[62:63], v[110:111]
	v_pk_fma_f32 v[56:57], v[12:13], v[96:97], v[56:57]
	s_and_b64 vcc, exec, s[4:5]
	v_pk_fma_f32 v[54:55], v[14:15], v[54:55], v[98:99]
	s_cbranch_vccz .Lrp139_n2_1
	v_mov_b32_e32 v88, 1.0
	s_branch .Lrp139_st_1

.Lrp139_st_1:
	v_ashrrev_i32_e32 v33, 31, v32
	v_lshlrev_b64 v[32:33], 11, v[32:33]
	v_lshl_add_u64 v[90:91], v[48:49], 0, v[32:33]
	v_cvt_pk_bf16_f32 v92, v46, v47
	v_cvt_pk_bf16_f32 v93, v44, v45
	global_store_dwordx2 v[90:91], v[92:93], off
	v_cvt_pk_bf16_f32 v92, v42, v43
	v_cvt_pk_bf16_f32 v93, v38, v39
	global_store_dwordx2 v[90:91], v[92:93], off offset:512
	v_cvt_pk_bf16_f32 v92, v62, v63
	v_cvt_pk_bf16_f32 v93, v60, v61
	global_store_dwordx2 v[90:91], v[92:93], off offset:1024
	v_cvt_pk_bf16_f32 v92, v56, v57
	v_cvt_pk_bf16_f32 v93, v54, v55
	v_pk_mul_f32 v[46:47], v[46:47], v[88:89] op_sel_hi:[1,0]
	v_pk_mul_f32 v[44:45], v[44:45], v[88:89] op_sel_hi:[1,0]
	v_pk_mul_f32 v[42:43], v[42:43], v[88:89] op_sel_hi:[1,0]
	v_pk_mul_f32 v[38:39], v[38:39], v[88:89] op_sel_hi:[1,0]
	v_pk_mul_f32 v[62:63], v[62:63], v[88:89] op_sel_hi:[1,0]
	v_pk_mul_f32 v[60:61], v[60:61], v[88:89] op_sel_hi:[1,0]
	v_pk_mul_f32 v[56:57], v[56:57], v[88:89] op_sel_hi:[1,0]
	v_pk_mul_f32 v[54:55], v[54:55], v[88:89] op_sel_hi:[1,0]
	v_pk_mul_f32 v[46:47], v[16:17], v[46:47]
	v_pk_mul_f32 v[44:45], v[18:19], v[44:45]
	v_pk_mul_f32 v[42:43], v[20:21], v[42:43]
	v_pk_mul_f32 v[38:39], v[22:23], v[38:39]
	v_pk_mul_f32 v[62:63], v[24:25], v[62:63]
	v_pk_mul_f32 v[60:61], v[26:27], v[60:61]
	v_pk_mul_f32 v[56:57], v[28:29], v[56:57]
	v_pk_mul_f32 v[54:55], v[30:31], v[54:55]
	v_lshl_add_u64 v[32:33], v[58:59], 0, v[32:33]
	v_cvt_pk_bf16_f32 v46, v46, v47
	v_cvt_pk_bf16_f32 v47, v44, v45
	v_cvt_pk_bf16_f32 v42, v42, v43
	v_cvt_pk_bf16_f32 v43, v38, v39
	v_cvt_pk_bf16_f32 v62, v62, v63
	v_cvt_pk_bf16_f32 v63, v60, v61
	v_cvt_pk_bf16_f32 v56, v56, v57
	v_cvt_pk_bf16_f32 v57, v54, v55
	global_store_dwordx2 v[90:91], v[92:93], off offset:1536
	global_store_dwordx2 v[32:33], v[46:47], off
	global_store_dwordx2 v[32:33], v[42:43], off offset:512
	global_store_dwordx2 v[32:33], v[62:63], off offset:1024
	global_store_dwordx2 v[32:33], v[56:57], off offset:1536
	v_subrev_u32_e32 v32, s70, v89
	v_cmp_lt_i32_e32 vcc, v125, v32
	s_or_b64 s[8:9], vcc, s[8:9]
	s_andn2_b64 exec, exec, s[8:9]
	s_cbranch_execz .LBB0_141
.Lrp139_top2:
	v_add_u32_e32 v89, s71, v32
	v_cmp_gt_i32_e32 vcc, v124, v89
	s_nop 1
	v_cndmask_b32_e32 v62, v32, v89, vcc
	v_ashrrev_i32_e32 v63, 31, v62
	v_lshlrev_b64 v[62:63], 11, v[62:63]
	v_lshl_add_u64 v[54:55], v[48:49], 0, v[62:63]
	s_waitcnt lgkmcnt(0)
	v_lshl_add_u64 v[38:39], v[52:53], 0, v[62:63]
	global_load_dwordx2 v[62:63], v[54:55], off
	global_load_dwordx2 v[60:61], v[54:55], off offset:512
	global_load_dwordx2 v[56:57], v[54:55], off offset:1024
	s_nop 0
	global_load_dwordx2 v[54:55], v[54:55], off offset:1536
	s_nop 0
	global_load_dwordx2 v[46:47], v[38:39], off
	global_load_dwordx2 v[44:45], v[38:39], off offset:512
	global_load_dwordx2 v[42:43], v[38:39], off offset:1024
	s_nop 0
	global_load_dwordx2 v[38:39], v[38:39], off offset:1536
	s_waitcnt vmcnt(32)
	v_lshlrev_b32_e32 v100, 16, v74
	v_and_b32_e32 v101, 0xffff0000, v74
	v_lshlrev_b32_e32 v96, 16, v75
	v_and_b32_e32 v97, 0xffff0000, v75
	v_pk_mul_f32 v[74:75], v[100:101], v[100:101]
	v_pk_mul_f32 v[98:99], v[96:97], v[96:97]
	v_add_f32_e32 v74, v74, v75
	v_lshlrev_b32_e32 v106, 16, v76
	v_and_b32_e32 v107, 0xffff0000, v76
	v_add_f32_e32 v74, v98, v74
	v_lshlrev_b32_e32 v102, 16, v77
	v_and_b32_e32 v103, 0xffff0000, v77
	v_pk_mul_f32 v[76:77], v[106:107], v[106:107]
	v_add_f32_e32 v74, v99, v74
	v_add_f32_e32 v76, v76, v74
	v_pk_mul_f32 v[104:105], v[102:103], v[102:103]
	v_add_f32_e32 v76, v77, v76
	v_lshlrev_b32_e32 v112, 16, v78
	v_and_b32_e32 v113, 0xffff0000, v78
	v_add_f32_e32 v76, v104, v76
	v_lshlrev_b32_e32 v108, 16, v79
	v_and_b32_e32 v109, 0xffff0000, v79
	v_pk_mul_f32 v[78:79], v[112:113], v[112:113]
	v_add_f32_e32 v76, v105, v76
	v_add_f32_e32 v78, v78, v76
	v_pk_mul_f32 v[110:111], v[108:109], v[108:109]
	v_add_f32_e32 v78, v79, v78
	v_lshlrev_b32_e32 v114, 16, v80
	v_and_b32_e32 v115, 0xffff0000, v80
	v_add_f32_e32 v78, v110, v78
	v_and_b32_e32 v33, 64, v207
	v_and_b32_e32 v95, 0xffff0000, v81
	v_lshlrev_b32_e32 v94, 16, v81
	v_pk_mul_f32 v[80:81], v[114:115], v[114:115]
	v_add_f32_e32 v78, v111, v78
	v_add_u32_e32 v116, 64, v33
	v_xor_b32_e32 v33, 32, v207
	v_add_f32_e32 v80, v80, v78
	v_cmp_lt_i32_e32 vcc, v33, v116
	v_pk_mul_f32 v[92:93], v[94:95], v[94:95]
	v_add_f32_e32 v80, v81, v80
	v_cndmask_b32_e32 v33, v207, v33, vcc
	v_add_f32_e32 v80, v92, v80
	v_lshlrev_b32_e32 v33, 2, v33
	v_add_f32_e32 v80, v93, v80
	ds_bpermute_b32 v81, v33, v80
	v_xor_b32_e32 v88, 16, v207
	v_cmp_lt_i32_e32 vcc, v88, v116
	v_xor_b32_e32 v90, 8, v207
	v_xor_b32_e32 v91, 4, v207
	v_cndmask_b32_e32 v88, v207, v88, vcc
	v_lshlrev_b32_e32 v88, 2, v88
	s_waitcnt lgkmcnt(0)
	v_add_f32_e32 v80, v80, v81
	ds_bpermute_b32 v81, v88, v80
	v_cmp_lt_i32_e32 vcc, v90, v116
	v_and_b32_e32 v99, 0xffff0000, v73
	v_lshlrev_b32_e32 v98, 16, v73
	v_cndmask_b32_e32 v90, v207, v90, vcc
	v_lshlrev_b32_e32 v90, 2, v90
	s_waitcnt lgkmcnt(0)
	v_add_f32_e32 v80, v80, v81
	ds_bpermute_b32 v81, v90, v80
	v_cmp_lt_i32_e32 vcc, v91, v116
	v_lshlrev_b32_e32 v104, 16, v68
	v_and_b32_e32 v105, 0xffff0000, v68
	v_cndmask_b32_e32 v78, v207, v91, vcc
	v_lshlrev_b32_e32 v91, 2, v78
	s_waitcnt lgkmcnt(0)
	v_add_f32_e32 v79, v80, v81
	ds_bpermute_b32 v76, v91, v79
	v_xor_b32_e32 v78, 2, v207
	v_cmp_lt_i32_e32 vcc, v78, v116
	v_lshlrev_b32_e32 v80, 16, v67
	v_and_b32_e32 v81, 0xffff0000, v67
	v_cndmask_b32_e32 v78, v207, v78, vcc
	v_lshlrev_b32_e32 v92, 2, v78
	s_waitcnt lgkmcnt(0)
	v_add_f32_e32 v73, v79, v76
	ds_bpermute_b32 v76, v92, v73
	v_xor_b32_e32 v78, 1, v207
	v_cmp_lt_i32_e32 vcc, v78, v116
	v_and_b32_e32 v79, 0xffff0000, v66
	v_and_b32_e32 v67, 0xffff0000, v69
	v_cndmask_b32_e32 v78, v207, v78, vcc
	v_lshlrev_b32_e32 v93, 2, v78
	s_waitcnt lgkmcnt(0)
	v_add_f32_e32 v73, v73, v76
	ds_bpermute_b32 v76, v93, v73
	v_lshlrev_b32_e32 v78, 16, v66
	v_lshlrev_b32_e32 v66, 16, v69
	v_lshlrev_b32_e32 v68, 16, v71
	v_and_b32_e32 v69, 0xffff0000, v71
	s_waitcnt lgkmcnt(0)
	v_add_f32_e32 v71, v73, v76
	v_fmamk_f32 v71, v71, 0x3a800000, v205
	v_mul_f32_e32 v73, 0x4b800000, v71
	v_cmp_gt_f32_e32 vcc, s30, v71
	v_lshlrev_b32_e32 v110, 16, v70
	v_and_b32_e32 v111, 0xffff0000, v70
	v_cndmask_b32_e32 v71, v71, v73, vcc
	v_rsq_f32_e32 v73, v71
	v_lshlrev_b32_e32 v70, 16, v72
	v_and_b32_e32 v71, 0xffff0000, v72
	v_mul_f32_e32 v72, 0x45800000, v73
	v_cndmask_b32_e32 v72, v73, v72, vcc
	v_pk_mul_f32 v[76:77], v[72:73], v[100:101] op_sel_hi:[0,1]
	v_pk_fma_f32 v[74:75], v[0:1], v[76:77], v[78:79]
	v_pk_mul_f32 v[78:79], v[72:73], v[96:97] op_sel_hi:[0,1]
	v_pk_fma_f32 v[76:77], v[2:3], v[78:79], v[80:81]
	v_pk_mul_f32 v[80:81], v[72:73], v[106:107] op_sel_hi:[0,1]
	v_pk_fma_f32 v[78:79], v[4:5], v[80:81], v[104:105]
	v_pk_mul_f32 v[80:81], v[72:73], v[102:103] op_sel_hi:[0,1]
	v_pk_mul_f32 v[96:97], v[72:73], v[108:109] op_sel_hi:[0,1]
	v_pk_fma_f32 v[80:81], v[6:7], v[80:81], v[66:67]
	v_pk_mul_f32 v[66:67], v[72:73], v[112:113] op_sel_hi:[0,1]
	v_pk_fma_f32 v[68:69], v[10:11], v[96:97], v[68:69]
	v_pk_mul_f32 v[96:97], v[72:73], v[114:115] op_sel_hi:[0,1]
	v_pk_mul_f32 v[72:73], v[72:73], v[94:95] op_sel_hi:[0,1]
	v_pk_fma_f32 v[66:67], v[8:9], v[66:67], v[110:111]
	v_pk_fma_f32 v[70:71], v[12:13], v[96:97], v[70:71]
	s_and_b64 vcc, exec, s[4:5]
	v_pk_fma_f32 v[72:73], v[14:15], v[72:73], v[98:99]
	s_cbranch_vccz .Lrp139_n2_2
	v_mov_b32_e32 v88, 1.0
	s_branch .Lrp139_st_2

.Lrp139_st_2:
	v_ashrrev_i32_e32 v33, 31, v32
	v_lshlrev_b64 v[32:33], 11, v[32:33]
	v_lshl_add_u64 v[90:91], v[48:49], 0, v[32:33]
	v_cvt_pk_bf16_f32 v92, v74, v75
	v_cvt_pk_bf16_f32 v93, v76, v77
	global_store_dwordx2 v[90:91], v[92:93], off
	v_cvt_pk_bf16_f32 v92, v78, v79
	v_cvt_pk_bf16_f32 v93, v80, v81
	global_store_dwordx2 v[90:91], v[92:93], off offset:512
	v_cvt_pk_bf16_f32 v92, v66, v67
	v_cvt_pk_bf16_f32 v93, v68, v69
	global_store_dwordx2 v[90:91], v[92:93], off offset:1024
	v_cvt_pk_bf16_f32 v92, v70, v71
	v_cvt_pk_bf16_f32 v93, v72, v73
	v_pk_mul_f32 v[74:75], v[74:75], v[88:89] op_sel_hi:[1,0]
	v_pk_mul_f32 v[76:77], v[76:77], v[88:89] op_sel_hi:[1,0]
	v_pk_mul_f32 v[78:79], v[78:79], v[88:89] op_sel_hi:[1,0]
	v_pk_mul_f32 v[80:81], v[80:81], v[88:89] op_sel_hi:[1,0]
	v_pk_mul_f32 v[66:67], v[66:67], v[88:89] op_sel_hi:[1,0]
	v_pk_mul_f32 v[68:69], v[68:69], v[88:89] op_sel_hi:[1,0]
	v_pk_mul_f32 v[70:71], v[70:71], v[88:89] op_sel_hi:[1,0]
	v_pk_mul_f32 v[72:73], v[72:73], v[88:89] op_sel_hi:[1,0]
	v_pk_mul_f32 v[74:75], v[16:17], v[74:75]
	v_pk_mul_f32 v[76:77], v[18:19], v[76:77]
	v_pk_mul_f32 v[78:79], v[20:21], v[78:79]
	v_pk_mul_f32 v[80:81], v[22:23], v[80:81]
	v_pk_mul_f32 v[66:67], v[24:25], v[66:67]
	v_pk_mul_f32 v[68:69], v[26:27], v[68:69]
	v_pk_mul_f32 v[70:71], v[28:29], v[70:71]
	v_pk_mul_f32 v[72:73], v[30:31], v[72:73]
	v_lshl_add_u64 v[32:33], v[58:59], 0, v[32:33]
	v_cvt_pk_bf16_f32 v74, v74, v75
	v_cvt_pk_bf16_f32 v75, v76, v77
	v_cvt_pk_bf16_f32 v78, v78, v79
	v_cvt_pk_bf16_f32 v79, v80, v81
	v_cvt_pk_bf16_f32 v66, v66, v67
	v_cvt_pk_bf16_f32 v67, v68, v69
	v_cvt_pk_bf16_f32 v70, v70, v71
	v_cvt_pk_bf16_f32 v71, v72, v73
	global_store_dwordx2 v[90:91], v[92:93], off offset:1536
	global_store_dwordx2 v[32:33], v[74:75], off
	global_store_dwordx2 v[32:33], v[78:79], off offset:512
	global_store_dwordx2 v[32:33], v[66:67], off offset:1024
	global_store_dwordx2 v[32:33], v[70:71], off offset:1536
	v_subrev_u32_e32 v32, s70, v89
	v_cmp_lt_i32_e32 vcc, v125, v32
	s_or_b64 s[8:9], vcc, s[8:9]
	s_andn2_b64 exec, exec, s[8:9]
	s_cbranch_execz .LBB0_141
	s_branch .LBB0_139

.LBB0_343:
	s_nop 0
	v_readlane_b32 s2, v255, 24
	v_readlane_b32 s3, v255, 25
	s_and_b64 vcc, exec, s[2:3]
	s_cbranch_vccz .LBB0_363
	v_mov_b32_e32 v0, v204
	v_readlane_b32 s0, v255, 20
	v_ashrrev_i32_e32 v0, 6, v0
	s_add_i32 s0, s0, -16
	v_add_u32_e32 v32, s69, v0
	s_cmp_eq_u32 s70, 1
	s_cbranch_scc0 .Lrm2_old
	v_lshlrev_b32_e32 v32, 4, v32
	v_add_u32_e32 v124, 16, v32
	s_branch .Lrm2_done

.Lrm2_done:
	v_add_u32_e32 v125, -1, v124
	s_cmp_gt_u32 s0, 14
	s_mov_b64 s[2:3], -1
	v_cmp_gt_i32_e32 vcc, v124, v32
	s_cbranch_scc0 .LBB0_355
	v_mov_b32_e32 v0, v204
	s_and_saveexec_b64 s[2:3], vcc
	s_cbranch_execz .LBB0_354
	v_readlane_b32 s8, v252, 0
	v_readlane_b32 s9, v252, 1
	v_ashrrev_i32_e32 v33, 31, v32
	v_readlane_b32 s8, v254, 32
	v_lshlrev_b32_e32 v0, 2, v0
	v_lshlrev_b64 v[2:3], 11, v[32:33]
	v_readlane_b32 s9, v254, 33
	v_and_b32_e32 v6, 0xfc, v0
	v_readlane_b32 s4, v255, 21
	v_lshl_add_u64 v[4:5], s[8:9], 0, v[2:3]
	v_lshlrev_b32_e32 v188, 1, v6
	s_lshl_b32 s6, s4, 10
	v_lshl_add_u64 v[0:1], v[4:5], 0, v[188:189]
	v_lshl_add_u64 v[2:3], s[88:89], 0, v[2:3]
	v_readlane_b32 s5, v255, 22
	s_ashr_i32 s7, s6, 31
	v_lshl_add_u64 v[2:3], v[2:3], 0, v[188:189]
	global_load_dwordx2 v[40:41], v[0:1], off
	global_load_dwordx2 v[38:39], v[0:1], off offset:512
	global_load_dwordx2 v[34:35], v[0:1], off offset:1024
	global_load_dwordx2 v[36:37], v[0:1], off offset:1536
	global_load_dwordx2 v[88:89], v[2:3], off
	global_load_dwordx2 v[84:85], v[2:3], off offset:512
	global_load_dwordx2 v[66:67], v[2:3], off offset:1024
	global_load_dwordx2 v[64:65], v[2:3], off offset:1536
	s_lshl_b64 s[4:5], s[6:7], 2
	v_readlane_b32 s14, v252, 6
	v_readlane_b32 s15, v252, 7
	s_add_u32 s4, s14, s4
	s_addc_u32 s5, s15, s5
	v_lshlrev_b32_e32 v28, 2, v6
	global_load_dwordx4 v[0:3], v28, s[4:5]
	global_load_dwordx4 v[4:7], v28, s[4:5] offset:1024
	global_load_dwordx4 v[8:11], v28, s[4:5] offset:2048
	global_load_dwordx4 v[12:15], v28, s[4:5] offset:3072
	v_readlane_b32 s8, v254, 6
	v_readlane_b32 s9, v254, 7
	s_andn2_b64 vcc, exec, s[8:9]
	v_readlane_b32 s10, v252, 2
	v_cndmask_b32_e64 v16, 0, 1, s[8:9]
	v_cmp_ne_u32_e64 s[4:5], 1, v16
	v_readlane_b32 s11, v252, 3
	v_readlane_b32 s12, v252, 4
	v_readlane_b32 s13, v252, 5
	s_cbranch_vccnz .LBB0_348
	s_addk_i32 s6, 0x400
	s_ashr_i32 s7, s6, 31
	s_lshl_b64 s[6:7], s[6:7], 2
	v_readlane_b32 s8, v252, 12
	v_readlane_b32 s9, v252, 13
	s_add_u32 s6, s8, s6
	s_addc_u32 s7, s9, s7
	global_load_dwordx4 v[16:19], v28, s[6:7]
	global_load_dwordx4 v[20:23], v28, s[6:7] offset:1024
	global_load_dwordx4 v[24:27], v28, s[6:7] offset:2048
	s_nop 0
	global_load_dwordx4 v[28:31], v28, s[6:7] offset:3072
	v_readlane_b32 s10, v252, 14
	v_readlane_b32 s11, v252, 15
	v_readlane_b32 s12, v252, 16
	v_readlane_b32 s13, v252, 17
	v_readlane_b32 s14, v252, 18
	v_readlane_b32 s15, v252, 19
	v_readlane_b32 s16, v252, 20
	v_readlane_b32 s17, v252, 21
	v_readlane_b32 s18, v252, 22
	v_readlane_b32 s19, v252, 23
	v_readlane_b32 s20, v252, 24
	v_readlane_b32 s21, v252, 25
	v_readlane_b32 s22, v252, 26
	v_readlane_b32 s23, v252, 27
	s_branch .LBB0_349

.LBB0_349:
	v_add_u32_e32 v33, s70, v32
	v_cmp_gt_i32_e32 vcc, v124, v33
	v_readlane_b32 s6, v254, 32
	v_readlane_b32 s7, v254, 33
	v_cndmask_b32_e32 v42, v32, v33, vcc
	v_ashrrev_i32_e32 v43, 31, v42
	v_lshlrev_b64 v[50:51], 11, v[42:43]
	v_lshl_add_u64 v[42:43], s[88:89], 0, v[50:51]
	v_lshl_add_u64 v[50:51], s[6:7], 0, v[50:51]
	v_lshl_add_u64 v[48:49], v[42:43], 0, v[188:189]
	v_lshl_add_u64 v[50:51], v[50:51], 0, v[188:189]
	global_load_dwordx2 v[42:43], v[48:49], off offset:1536
	global_load_dwordx2 v[44:45], v[48:49], off offset:1024
	global_load_dwordx2 v[46:47], v[48:49], off offset:512
	s_nop 0
	global_load_dwordx2 v[48:49], v[48:49], off
	s_nop 0
	global_load_dwordx2 v[54:55], v[50:51], off offset:1536
	global_load_dwordx2 v[58:59], v[50:51], off offset:1024
	global_load_dwordx2 v[60:61], v[50:51], off offset:512
	global_load_dwordx2 v[62:63], v[50:51], off
	v_lshl_add_u64 v[50:51], s[6:7], 0, v[188:189]
	v_readlane_b32 s6, v253, 2
	v_readlane_b32 s7, v253, 3
	v_lshl_add_u64 v[52:53], s[88:89], 0, v[188:189]
	v_mov_b32_e32 v86, v32
	v_lshl_add_u64 v[56:57], s[6:7], 0, v[188:189]
	s_mov_b64 s[6:7], 0
	s_waitcnt vmcnt(0)
	s_branch .LBB0_352
.LBB0_352:
	v_add_u32_e32 v33, s71, v86
	v_cmp_gt_i32_e32 vcc, v124, v33
	s_nop 1
	v_cndmask_b32_e32 v68, v86, v33, vcc
	v_ashrrev_i32_e32 v69, 31, v68
	v_lshlrev_b64 v[68:69], 11, v[68:69]
	v_lshl_add_u64 v[74:75], v[50:51], 0, v[68:69]
	v_lshl_add_u64 v[82:83], v[52:53], 0, v[68:69]
	global_load_dwordx2 v[68:69], v[74:75], off
	global_load_dwordx2 v[70:71], v[74:75], off offset:512
	global_load_dwordx2 v[72:73], v[74:75], off offset:1024
	s_nop 0
	global_load_dwordx2 v[74:75], v[74:75], off offset:1536
	s_nop 0
	global_load_dwordx2 v[76:77], v[82:83], off
	global_load_dwordx2 v[78:79], v[82:83], off offset:512
	s_waitcnt lgkmcnt(0)
	global_load_dwordx2 v[80:81], v[82:83], off offset:1024
	s_nop 0
	global_load_dwordx2 v[82:83], v[82:83], off offset:1536
	s_waitcnt vmcnt(32)
	v_lshlrev_b32_e32 v100, 16, v88
	v_and_b32_e32 v101, 0xffff0000, v88
	v_lshlrev_b32_e32 v98, 16, v89
	v_and_b32_e32 v99, 0xffff0000, v89
	v_pk_mul_f32 v[88:89], v[100:101], v[100:101]
	v_pk_mul_f32 v[94:95], v[98:99], v[98:99]
	v_add_f32_e32 v88, v88, v89
	v_lshlrev_b32_e32 v106, 16, v84
	v_and_b32_e32 v107, 0xffff0000, v84
	v_add_f32_e32 v88, v94, v88
	v_lshlrev_b32_e32 v102, 16, v85
	v_and_b32_e32 v103, 0xffff0000, v85
	v_pk_mul_f32 v[84:85], v[106:107], v[106:107]
	v_add_f32_e32 v88, v95, v88
	v_add_f32_e32 v84, v84, v88
	v_pk_mul_f32 v[104:105], v[102:103], v[102:103]
	v_add_f32_e32 v84, v85, v84
	v_lshlrev_b32_e32 v112, 16, v66
	v_and_b32_e32 v113, 0xffff0000, v66
	v_add_f32_e32 v84, v104, v84
	v_lshlrev_b32_e32 v108, 16, v67
	v_and_b32_e32 v109, 0xffff0000, v67
	v_pk_mul_f32 v[66:67], v[112:113], v[112:113]
	v_add_f32_e32 v84, v105, v84
	v_add_f32_e32 v66, v66, v84
	v_pk_mul_f32 v[110:111], v[108:109], v[108:109]
	v_add_f32_e32 v66, v67, v66
	v_lshlrev_b32_e32 v114, 16, v64
	v_and_b32_e32 v115, 0xffff0000, v64
	v_add_f32_e32 v66, v110, v66
	v_and_b32_e32 v87, 64, v207
	v_and_b32_e32 v97, 0xffff0000, v65
	v_lshlrev_b32_e32 v96, 16, v65
	v_pk_mul_f32 v[64:65], v[114:115], v[114:115]
	v_add_f32_e32 v66, v111, v66
	v_add_u32_e32 v116, 64, v87
	v_xor_b32_e32 v87, 32, v207
	v_add_f32_e32 v64, v64, v66
	v_cmp_lt_i32_e32 vcc, v87, v116
	v_pk_mul_f32 v[92:93], v[96:97], v[96:97]
	v_add_f32_e32 v64, v65, v64
	v_cndmask_b32_e32 v87, v207, v87, vcc
	v_add_f32_e32 v64, v92, v64
	v_lshlrev_b32_e32 v87, 2, v87
	v_add_f32_e32 v64, v93, v64
	ds_bpermute_b32 v65, v87, v64
	v_xor_b32_e32 v90, 16, v207
	v_cmp_lt_i32_e32 vcc, v90, v116
	v_xor_b32_e32 v91, 8, v207
	v_xor_b32_e32 v117, 4, v207
	v_cndmask_b32_e32 v90, v207, v90, vcc
	v_lshlrev_b32_e32 v90, 2, v90
	s_waitcnt lgkmcnt(0)
	v_add_f32_e32 v64, v64, v65
	ds_bpermute_b32 v65, v90, v64
	v_cmp_lt_i32_e32 vcc, v91, v116
	v_and_b32_e32 v105, 0xffff0000, v37
	v_lshlrev_b32_e32 v104, 16, v37
	v_cndmask_b32_e32 v91, v207, v91, vcc
	v_lshlrev_b32_e32 v91, 2, v91
	s_waitcnt lgkmcnt(0)
	v_add_f32_e32 v64, v64, v65
	ds_bpermute_b32 v65, v91, v64
	v_cmp_lt_i32_e32 vcc, v117, v116
	v_lshlrev_b32_e32 v110, 16, v38
	v_and_b32_e32 v111, 0xffff0000, v38
	v_cndmask_b32_e32 v66, v207, v117, vcc
	v_lshlrev_b32_e32 v92, 2, v66
	s_waitcnt lgkmcnt(0)
	v_add_f32_e32 v67, v64, v65
	ds_bpermute_b32 v84, v92, v67
	v_xor_b32_e32 v66, 2, v207
	v_cmp_lt_i32_e32 vcc, v66, v116
	v_lshlrev_b32_e32 v64, 16, v41
	v_and_b32_e32 v65, 0xffff0000, v41
	v_cndmask_b32_e32 v66, v207, v66, vcc
	v_lshlrev_b32_e32 v93, 2, v66
	s_waitcnt lgkmcnt(0)
	v_add_f32_e32 v37, v67, v84
	ds_bpermute_b32 v84, v93, v37
	v_xor_b32_e32 v66, 1, v207
	v_cmp_lt_i32_e32 vcc, v66, v116
	v_and_b32_e32 v67, 0xffff0000, v40
	v_and_b32_e32 v41, 0xffff0000, v39
	v_cndmask_b32_e32 v66, v207, v66, vcc
	v_lshlrev_b32_e32 v94, 2, v66
	s_waitcnt lgkmcnt(0)
	v_add_f32_e32 v37, v37, v84
	ds_bpermute_b32 v84, v94, v37
	v_lshlrev_b32_e32 v66, 16, v40
	v_lshlrev_b32_e32 v40, 16, v39
	v_lshlrev_b32_e32 v38, 16, v35
	v_and_b32_e32 v39, 0xffff0000, v35
	s_waitcnt lgkmcnt(0)
	v_add_f32_e32 v35, v37, v84
	v_fmamk_f32 v35, v35, 0x3a800000, v205
	v_mul_f32_e32 v37, 0x4b800000, v35
	v_cmp_gt_f32_e32 vcc, s30, v35
	v_lshlrev_b32_e32 v116, 16, v34
	v_and_b32_e32 v117, 0xffff0000, v34
	v_cndmask_b32_e32 v35, v35, v37, vcc
	v_rsq_f32_e32 v37, v35
	v_lshlrev_b32_e32 v34, 16, v36
	v_and_b32_e32 v35, 0xffff0000, v36
	v_mul_f32_e32 v36, 0x45800000, v37
	v_cndmask_b32_e32 v36, v37, v36, vcc
	v_pk_mul_f32 v[84:85], v[36:37], v[100:101] op_sel_hi:[0,1]
	v_pk_fma_f32 v[88:89], v[0:1], v[84:85], v[66:67]
	v_pk_mul_f32 v[66:67], v[36:37], v[98:99] op_sel_hi:[0,1]
	v_pk_fma_f32 v[84:85], v[2:3], v[66:67], v[64:65]
	v_pk_mul_f32 v[64:65], v[36:37], v[106:107] op_sel_hi:[0,1]
	v_pk_fma_f32 v[66:67], v[4:5], v[64:65], v[110:111]
	v_pk_mul_f32 v[64:65], v[36:37], v[102:103] op_sel_hi:[0,1]
	v_pk_mul_f32 v[98:99], v[36:37], v[108:109] op_sel_hi:[0,1]
	v_pk_fma_f32 v[64:65], v[6:7], v[64:65], v[40:41]
	v_pk_mul_f32 v[40:41], v[36:37], v[112:113] op_sel_hi:[0,1]
	v_pk_fma_f32 v[38:39], v[10:11], v[98:99], v[38:39]
	v_pk_mul_f32 v[98:99], v[36:37], v[114:115] op_sel_hi:[0,1]
	v_pk_mul_f32 v[36:37], v[36:37], v[96:97] op_sel_hi:[0,1]
	v_pk_fma_f32 v[40:41], v[8:9], v[40:41], v[116:117]
	v_pk_fma_f32 v[34:35], v[12:13], v[98:99], v[34:35]
	s_and_b64 vcc, exec, s[4:5]
	v_pk_fma_f32 v[36:37], v[14:15], v[36:37], v[104:105]
	s_cbranch_vccz .Lrp352_n2_0
	v_mov_b32_e32 v90, 1.0
	s_branch .Lrp352_st_0

.Lrp352_st_0:
	v_ashrrev_i32_e32 v87, 31, v86
	v_lshlrev_b64 v[86:87], 11, v[86:87]
	v_lshl_add_u64 v[92:93], v[56:57], 0, v[86:87]
	v_cvt_pk_bf16_f32 v94, v88, v89
	v_cvt_pk_bf16_f32 v95, v84, v85
	global_store_dwordx2 v[92:93], v[94:95], off
	v_cvt_pk_bf16_f32 v94, v66, v67
	v_cvt_pk_bf16_f32 v95, v64, v65
	global_store_dwordx2 v[92:93], v[94:95], off offset:512
	v_cvt_pk_bf16_f32 v94, v40, v41
	v_cvt_pk_bf16_f32 v95, v38, v39
	global_store_dwordx2 v[92:93], v[94:95], off offset:1024
	v_cvt_pk_bf16_f32 v94, v34, v35
	v_cvt_pk_bf16_f32 v95, v36, v37
	v_pk_mul_f32 v[88:89], v[88:89], v[90:91] op_sel_hi:[1,0]
	v_pk_mul_f32 v[84:85], v[84:85], v[90:91] op_sel_hi:[1,0]
	v_pk_mul_f32 v[66:67], v[66:67], v[90:91] op_sel_hi:[1,0]
	v_pk_mul_f32 v[64:65], v[64:65], v[90:91] op_sel_hi:[1,0]
	v_pk_mul_f32 v[40:41], v[40:41], v[90:91] op_sel_hi:[1,0]
	v_pk_mul_f32 v[38:39], v[38:39], v[90:91] op_sel_hi:[1,0]
	v_pk_mul_f32 v[34:35], v[34:35], v[90:91] op_sel_hi:[1,0]
	v_pk_mul_f32 v[36:37], v[36:37], v[90:91] op_sel_hi:[1,0]
	v_pk_mul_f32 v[88:89], v[16:17], v[88:89]
	v_pk_mul_f32 v[84:85], v[18:19], v[84:85]
	v_pk_mul_f32 v[66:67], v[20:21], v[66:67]
	v_pk_mul_f32 v[64:65], v[22:23], v[64:65]
	v_pk_mul_f32 v[40:41], v[24:25], v[40:41]
	v_pk_mul_f32 v[38:39], v[26:27], v[38:39]
	v_pk_mul_f32 v[34:35], v[28:29], v[34:35]
	v_pk_mul_f32 v[36:37], v[30:31], v[36:37]
	v_lshl_add_u64 v[86:87], v[50:51], 0, v[86:87]
	v_cvt_pk_bf16_f32 v88, v88, v89
	v_cvt_pk_bf16_f32 v89, v84, v85
	v_cvt_pk_bf16_f32 v66, v66, v67
	v_cvt_pk_bf16_f32 v67, v64, v65
	v_cvt_pk_bf16_f32 v40, v40, v41
	v_cvt_pk_bf16_f32 v41, v38, v39
	v_cvt_pk_bf16_f32 v34, v34, v35
	v_cvt_pk_bf16_f32 v35, v36, v37
	global_store_dwordx2 v[92:93], v[94:95], off offset:1536
	global_store_dwordx2 v[86:87], v[88:89], off
	global_store_dwordx2 v[86:87], v[66:67], off offset:512
	global_store_dwordx2 v[86:87], v[40:41], off offset:1024
	global_store_dwordx2 v[86:87], v[34:35], off offset:1536
	v_subrev_u32_e32 v86, s70, v33
	v_cmp_lt_i32_e32 vcc, v125, v86
	s_or_b64 s[6:7], vcc, s[6:7]
	s_andn2_b64 exec, exec, s[6:7]
	s_cbranch_execz .LBB0_354
.Lrp352_top1:
	v_add_u32_e32 v33, s71, v86
	v_cmp_gt_i32_e32 vcc, v124, v33
	s_nop 1
	v_cndmask_b32_e32 v40, v86, v33, vcc
	v_ashrrev_i32_e32 v41, 31, v40
	v_lshlrev_b64 v[40:41], 11, v[40:41]
	v_lshl_add_u64 v[36:37], v[50:51], 0, v[40:41]
	v_lshl_add_u64 v[64:65], v[52:53], 0, v[40:41]
	global_load_dwordx2 v[40:41], v[36:37], off
	global_load_dwordx2 v[38:39], v[36:37], off offset:512
	global_load_dwordx2 v[34:35], v[36:37], off offset:1024
	s_nop 0
	global_load_dwordx2 v[36:37], v[36:37], off offset:1536
	s_nop 0
	global_load_dwordx2 v[88:89], v[64:65], off
	global_load_dwordx2 v[84:85], v[64:65], off offset:512
	s_waitcnt lgkmcnt(0)
	global_load_dwordx2 v[66:67], v[64:65], off offset:1024
	s_nop 0
	global_load_dwordx2 v[64:65], v[64:65], off offset:1536
	s_waitcnt vmcnt(32)
	v_lshlrev_b32_e32 v100, 16, v48
	v_and_b32_e32 v101, 0xffff0000, v48
	v_lshlrev_b32_e32 v98, 16, v49
	v_and_b32_e32 v99, 0xffff0000, v49
	v_pk_mul_f32 v[48:49], v[100:101], v[100:101]
	v_pk_mul_f32 v[94:95], v[98:99], v[98:99]
	v_add_f32_e32 v48, v48, v49
	v_lshlrev_b32_e32 v106, 16, v46
	v_and_b32_e32 v107, 0xffff0000, v46
	v_add_f32_e32 v48, v94, v48
	v_lshlrev_b32_e32 v102, 16, v47
	v_and_b32_e32 v103, 0xffff0000, v47
	v_pk_mul_f32 v[46:47], v[106:107], v[106:107]
	v_add_f32_e32 v48, v95, v48
	v_add_f32_e32 v46, v46, v48
	v_pk_mul_f32 v[104:105], v[102:103], v[102:103]
	v_add_f32_e32 v46, v47, v46
	v_lshlrev_b32_e32 v112, 16, v44
	v_and_b32_e32 v113, 0xffff0000, v44
	v_add_f32_e32 v46, v104, v46
	v_lshlrev_b32_e32 v108, 16, v45
	v_and_b32_e32 v109, 0xffff0000, v45
	v_pk_mul_f32 v[44:45], v[112:113], v[112:113]
	v_add_f32_e32 v46, v105, v46
	v_add_f32_e32 v44, v44, v46
	v_pk_mul_f32 v[110:111], v[108:109], v[108:109]
	v_add_f32_e32 v44, v45, v44
	v_lshlrev_b32_e32 v114, 16, v42
	v_and_b32_e32 v115, 0xffff0000, v42
	v_add_f32_e32 v44, v110, v44
	v_and_b32_e32 v87, 64, v207
	v_and_b32_e32 v97, 0xffff0000, v43
	v_lshlrev_b32_e32 v96, 16, v43
	v_pk_mul_f32 v[42:43], v[114:115], v[114:115]
	v_add_f32_e32 v44, v111, v44
	v_add_u32_e32 v116, 64, v87
	v_xor_b32_e32 v87, 32, v207
	v_add_f32_e32 v42, v42, v44
	v_cmp_lt_i32_e32 vcc, v87, v116
	v_pk_mul_f32 v[92:93], v[96:97], v[96:97]
	v_add_f32_e32 v42, v43, v42
	v_cndmask_b32_e32 v87, v207, v87, vcc
	v_add_f32_e32 v42, v92, v42
	v_lshlrev_b32_e32 v87, 2, v87
	v_add_f32_e32 v42, v93, v42
	ds_bpermute_b32 v43, v87, v42
	v_xor_b32_e32 v90, 16, v207
	v_cmp_lt_i32_e32 vcc, v90, v116
	v_xor_b32_e32 v91, 8, v207
	v_xor_b32_e32 v117, 4, v207
	v_cndmask_b32_e32 v90, v207, v90, vcc
	v_lshlrev_b32_e32 v90, 2, v90
	s_waitcnt lgkmcnt(0)
	v_add_f32_e32 v42, v42, v43
	ds_bpermute_b32 v43, v90, v42
	v_cmp_lt_i32_e32 vcc, v91, v116
	v_and_b32_e32 v105, 0xffff0000, v55
	v_lshlrev_b32_e32 v104, 16, v55
	v_cndmask_b32_e32 v91, v207, v91, vcc
	v_lshlrev_b32_e32 v91, 2, v91
	s_waitcnt lgkmcnt(0)
	v_add_f32_e32 v42, v42, v43
	ds_bpermute_b32 v43, v91, v42
	v_cmp_lt_i32_e32 vcc, v117, v116
	v_lshlrev_b32_e32 v110, 16, v60
	v_and_b32_e32 v111, 0xffff0000, v60
	v_cndmask_b32_e32 v44, v207, v117, vcc
	v_lshlrev_b32_e32 v92, 2, v44
	s_waitcnt lgkmcnt(0)
	v_add_f32_e32 v45, v42, v43
	ds_bpermute_b32 v46, v92, v45
	v_xor_b32_e32 v44, 2, v207
	v_cmp_lt_i32_e32 vcc, v44, v116
	v_lshlrev_b32_e32 v42, 16, v63
	v_and_b32_e32 v43, 0xffff0000, v63
	v_cndmask_b32_e32 v44, v207, v44, vcc
	v_lshlrev_b32_e32 v93, 2, v44
	s_waitcnt lgkmcnt(0)
	v_add_f32_e32 v55, v45, v46
	ds_bpermute_b32 v46, v93, v55
	v_xor_b32_e32 v44, 1, v207
	v_cmp_lt_i32_e32 vcc, v44, v116
	v_and_b32_e32 v45, 0xffff0000, v62
	v_and_b32_e32 v63, 0xffff0000, v61
	v_cndmask_b32_e32 v44, v207, v44, vcc
	v_lshlrev_b32_e32 v94, 2, v44
	s_waitcnt lgkmcnt(0)
	v_add_f32_e32 v55, v55, v46
	ds_bpermute_b32 v46, v94, v55
	v_lshlrev_b32_e32 v44, 16, v62
	v_lshlrev_b32_e32 v62, 16, v61
	v_lshlrev_b32_e32 v60, 16, v59
	v_and_b32_e32 v61, 0xffff0000, v59
	s_waitcnt lgkmcnt(0)
	v_add_f32_e32 v59, v55, v46
	v_fmamk_f32 v59, v59, 0x3a800000, v205
	v_mul_f32_e32 v55, 0x4b800000, v59
	v_cmp_gt_f32_e32 vcc, s30, v59
	v_lshlrev_b32_e32 v116, 16, v58
	v_and_b32_e32 v117, 0xffff0000, v58
	v_cndmask_b32_e32 v59, v59, v55, vcc
	v_rsq_f32_e32 v55, v59
	v_lshlrev_b32_e32 v58, 16, v54
	v_and_b32_e32 v59, 0xffff0000, v54
	v_mul_f32_e32 v54, 0x45800000, v55
	v_cndmask_b32_e32 v54, v55, v54, vcc
	v_pk_mul_f32 v[46:47], v[54:55], v[100:101] op_sel_hi:[0,1]
	v_pk_fma_f32 v[48:49], v[0:1], v[46:47], v[44:45]
	v_pk_mul_f32 v[44:45], v[54:55], v[98:99] op_sel_hi:[0,1]
	v_pk_fma_f32 v[46:47], v[2:3], v[44:45], v[42:43]
	v_pk_mul_f32 v[42:43], v[54:55], v[106:107] op_sel_hi:[0,1]
	v_pk_fma_f32 v[44:45], v[4:5], v[42:43], v[110:111]
	v_pk_mul_f32 v[42:43], v[54:55], v[102:103] op_sel_hi:[0,1]
	v_pk_mul_f32 v[98:99], v[54:55], v[108:109] op_sel_hi:[0,1]
	v_pk_fma_f32 v[42:43], v[6:7], v[42:43], v[62:63]
	v_pk_mul_f32 v[62:63], v[54:55], v[112:113] op_sel_hi:[0,1]
	v_pk_fma_f32 v[60:61], v[10:11], v[98:99], v[60:61]
	v_pk_mul_f32 v[98:99], v[54:55], v[114:115] op_sel_hi:[0,1]
	v_pk_mul_f32 v[54:55], v[54:55], v[96:97] op_sel_hi:[0,1]
	v_pk_fma_f32 v[62:63], v[8:9], v[62:63], v[116:117]
	v_pk_fma_f32 v[58:59], v[12:13], v[98:99], v[58:59]
	s_and_b64 vcc, exec, s[4:5]
	v_pk_fma_f32 v[54:55], v[14:15], v[54:55], v[104:105]
	s_cbranch_vccz .Lrp352_n2_1
	v_mov_b32_e32 v90, 1.0
	s_branch .Lrp352_st_1

.Lrp352_st_1:
	v_ashrrev_i32_e32 v87, 31, v86
	v_lshlrev_b64 v[86:87], 11, v[86:87]
	v_lshl_add_u64 v[92:93], v[56:57], 0, v[86:87]
	v_cvt_pk_bf16_f32 v94, v48, v49
	v_cvt_pk_bf16_f32 v95, v46, v47
	global_store_dwordx2 v[92:93], v[94:95], off
	v_cvt_pk_bf16_f32 v94, v44, v45
	v_cvt_pk_bf16_f32 v95, v42, v43
	global_store_dwordx2 v[92:93], v[94:95], off offset:512
	v_cvt_pk_bf16_f32 v94, v62, v63
	v_cvt_pk_bf16_f32 v95, v60, v61
	global_store_dwordx2 v[92:93], v[94:95], off offset:1024
	v_cvt_pk_bf16_f32 v94, v58, v59
	v_cvt_pk_bf16_f32 v95, v54, v55
	v_pk_mul_f32 v[48:49], v[48:49], v[90:91] op_sel_hi:[1,0]
	v_pk_mul_f32 v[46:47], v[46:47], v[90:91] op_sel_hi:[1,0]
	v_pk_mul_f32 v[44:45], v[44:45], v[90:91] op_sel_hi:[1,0]
	v_pk_mul_f32 v[42:43], v[42:43], v[90:91] op_sel_hi:[1,0]
	v_pk_mul_f32 v[62:63], v[62:63], v[90:91] op_sel_hi:[1,0]
	v_pk_mul_f32 v[60:61], v[60:61], v[90:91] op_sel_hi:[1,0]
	v_pk_mul_f32 v[58:59], v[58:59], v[90:91] op_sel_hi:[1,0]
	v_pk_mul_f32 v[54:55], v[54:55], v[90:91] op_sel_hi:[1,0]
	v_pk_mul_f32 v[48:49], v[16:17], v[48:49]
	v_pk_mul_f32 v[46:47], v[18:19], v[46:47]
	v_pk_mul_f32 v[44:45], v[20:21], v[44:45]
	v_pk_mul_f32 v[42:43], v[22:23], v[42:43]
	v_pk_mul_f32 v[62:63], v[24:25], v[62:63]
	v_pk_mul_f32 v[60:61], v[26:27], v[60:61]
	v_pk_mul_f32 v[58:59], v[28:29], v[58:59]
	v_pk_mul_f32 v[54:55], v[30:31], v[54:55]
	v_lshl_add_u64 v[86:87], v[50:51], 0, v[86:87]
	v_cvt_pk_bf16_f32 v48, v48, v49
	v_cvt_pk_bf16_f32 v49, v46, v47
	v_cvt_pk_bf16_f32 v44, v44, v45
	v_cvt_pk_bf16_f32 v45, v42, v43
	v_cvt_pk_bf16_f32 v62, v62, v63
	v_cvt_pk_bf16_f32 v63, v60, v61
	v_cvt_pk_bf16_f32 v58, v58, v59
	v_cvt_pk_bf16_f32 v59, v54, v55
	global_store_dwordx2 v[92:93], v[94:95], off offset:1536
	global_store_dwordx2 v[86:87], v[48:49], off
	global_store_dwordx2 v[86:87], v[44:45], off offset:512
	global_store_dwordx2 v[86:87], v[62:63], off offset:1024
	global_store_dwordx2 v[86:87], v[58:59], off offset:1536
	v_subrev_u32_e32 v86, s70, v33
	v_cmp_lt_i32_e32 vcc, v125, v86
	s_or_b64 s[6:7], vcc, s[6:7]
	s_andn2_b64 exec, exec, s[6:7]
	s_cbranch_execz .LBB0_354
.Lrp352_top2:
	v_add_u32_e32 v33, s71, v86
	v_cmp_gt_i32_e32 vcc, v124, v33
	s_nop 1
	v_cndmask_b32_e32 v62, v86, v33, vcc
	v_ashrrev_i32_e32 v63, 31, v62
	v_lshlrev_b64 v[62:63], 11, v[62:63]
	v_lshl_add_u64 v[54:55], v[50:51], 0, v[62:63]
	v_lshl_add_u64 v[42:43], v[52:53], 0, v[62:63]
	global_load_dwordx2 v[62:63], v[54:55], off
	global_load_dwordx2 v[60:61], v[54:55], off offset:512
	global_load_dwordx2 v[58:59], v[54:55], off offset:1024
	s_nop 0
	global_load_dwordx2 v[54:55], v[54:55], off offset:1536
	s_nop 0
	global_load_dwordx2 v[48:49], v[42:43], off
	global_load_dwordx2 v[46:47], v[42:43], off offset:512
	s_waitcnt lgkmcnt(0)
	global_load_dwordx2 v[44:45], v[42:43], off offset:1024
	s_nop 0
	global_load_dwordx2 v[42:43], v[42:43], off offset:1536
	s_waitcnt vmcnt(32)
	v_lshlrev_b32_e32 v100, 16, v76
	v_and_b32_e32 v101, 0xffff0000, v76
	v_lshlrev_b32_e32 v98, 16, v77
	v_and_b32_e32 v99, 0xffff0000, v77
	v_pk_mul_f32 v[76:77], v[100:101], v[100:101]
	v_pk_mul_f32 v[94:95], v[98:99], v[98:99]
	v_add_f32_e32 v76, v76, v77
	v_lshlrev_b32_e32 v106, 16, v78
	v_and_b32_e32 v107, 0xffff0000, v78
	v_add_f32_e32 v76, v94, v76
	v_lshlrev_b32_e32 v102, 16, v79
	v_and_b32_e32 v103, 0xffff0000, v79
	v_pk_mul_f32 v[78:79], v[106:107], v[106:107]
	v_add_f32_e32 v76, v95, v76
	v_add_f32_e32 v78, v78, v76
	v_pk_mul_f32 v[104:105], v[102:103], v[102:103]
	v_add_f32_e32 v78, v79, v78
	v_lshlrev_b32_e32 v112, 16, v80
	v_and_b32_e32 v113, 0xffff0000, v80
	v_add_f32_e32 v78, v104, v78
	v_lshlrev_b32_e32 v108, 16, v81
	v_and_b32_e32 v109, 0xffff0000, v81
	v_pk_mul_f32 v[80:81], v[112:113], v[112:113]
	v_add_f32_e32 v78, v105, v78
	v_add_f32_e32 v80, v80, v78
	v_pk_mul_f32 v[110:111], v[108:109], v[108:109]
	v_add_f32_e32 v80, v81, v80
	v_lshlrev_b32_e32 v114, 16, v82
	v_and_b32_e32 v115, 0xffff0000, v82
	v_add_f32_e32 v80, v110, v80
	v_and_b32_e32 v87, 64, v207
	v_and_b32_e32 v97, 0xffff0000, v83
	v_lshlrev_b32_e32 v96, 16, v83
	v_pk_mul_f32 v[82:83], v[114:115], v[114:115]
	v_add_f32_e32 v80, v111, v80
	v_add_u32_e32 v116, 64, v87
	v_xor_b32_e32 v87, 32, v207
	v_add_f32_e32 v82, v82, v80
	v_cmp_lt_i32_e32 vcc, v87, v116
	v_pk_mul_f32 v[92:93], v[96:97], v[96:97]
	v_add_f32_e32 v82, v83, v82
	v_cndmask_b32_e32 v87, v207, v87, vcc
	v_add_f32_e32 v82, v92, v82
	v_lshlrev_b32_e32 v87, 2, v87
	v_add_f32_e32 v82, v93, v82
	ds_bpermute_b32 v83, v87, v82
	v_xor_b32_e32 v90, 16, v207
	v_cmp_lt_i32_e32 vcc, v90, v116
	v_xor_b32_e32 v91, 8, v207
	v_xor_b32_e32 v117, 4, v207
	v_cndmask_b32_e32 v90, v207, v90, vcc
	v_lshlrev_b32_e32 v90, 2, v90
	s_waitcnt lgkmcnt(0)
	v_add_f32_e32 v82, v82, v83
	ds_bpermute_b32 v83, v90, v82
	v_cmp_lt_i32_e32 vcc, v91, v116
	v_and_b32_e32 v105, 0xffff0000, v75
	v_lshlrev_b32_e32 v104, 16, v75
	v_cndmask_b32_e32 v91, v207, v91, vcc
	v_lshlrev_b32_e32 v91, 2, v91
	s_waitcnt lgkmcnt(0)
	v_add_f32_e32 v82, v82, v83
	ds_bpermute_b32 v83, v91, v82
	v_cmp_lt_i32_e32 vcc, v117, v116
	v_lshlrev_b32_e32 v110, 16, v70
	v_and_b32_e32 v111, 0xffff0000, v70
	v_cndmask_b32_e32 v80, v207, v117, vcc
	v_lshlrev_b32_e32 v92, 2, v80
	s_waitcnt lgkmcnt(0)
	v_add_f32_e32 v81, v82, v83
	ds_bpermute_b32 v78, v92, v81
	v_xor_b32_e32 v80, 2, v207
	v_cmp_lt_i32_e32 vcc, v80, v116
	v_lshlrev_b32_e32 v82, 16, v69
	v_and_b32_e32 v83, 0xffff0000, v69
	v_cndmask_b32_e32 v80, v207, v80, vcc
	v_lshlrev_b32_e32 v93, 2, v80
	s_waitcnt lgkmcnt(0)
	v_add_f32_e32 v75, v81, v78
	ds_bpermute_b32 v78, v93, v75
	v_xor_b32_e32 v80, 1, v207
	v_cmp_lt_i32_e32 vcc, v80, v116
	v_and_b32_e32 v81, 0xffff0000, v68
	v_and_b32_e32 v69, 0xffff0000, v71
	v_cndmask_b32_e32 v80, v207, v80, vcc
	v_lshlrev_b32_e32 v94, 2, v80
	s_waitcnt lgkmcnt(0)
	v_add_f32_e32 v75, v75, v78
	ds_bpermute_b32 v78, v94, v75
	v_lshlrev_b32_e32 v80, 16, v68
	v_lshlrev_b32_e32 v68, 16, v71
	v_lshlrev_b32_e32 v70, 16, v73
	v_and_b32_e32 v71, 0xffff0000, v73
	s_waitcnt lgkmcnt(0)
	v_add_f32_e32 v73, v75, v78
	v_fmamk_f32 v73, v73, 0x3a800000, v205
	v_mul_f32_e32 v75, 0x4b800000, v73
	v_cmp_gt_f32_e32 vcc, s30, v73
	v_lshlrev_b32_e32 v116, 16, v72
	v_and_b32_e32 v117, 0xffff0000, v72
	v_cndmask_b32_e32 v73, v73, v75, vcc
	v_rsq_f32_e32 v75, v73
	v_lshlrev_b32_e32 v72, 16, v74
	v_and_b32_e32 v73, 0xffff0000, v74
	v_mul_f32_e32 v74, 0x45800000, v75
	v_cndmask_b32_e32 v74, v75, v74, vcc
	v_pk_mul_f32 v[78:79], v[74:75], v[100:101] op_sel_hi:[0,1]
	v_pk_fma_f32 v[76:77], v[0:1], v[78:79], v[80:81]
	v_pk_mul_f32 v[80:81], v[74:75], v[98:99] op_sel_hi:[0,1]
	v_pk_fma_f32 v[78:79], v[2:3], v[80:81], v[82:83]
	v_pk_mul_f32 v[82:83], v[74:75], v[106:107] op_sel_hi:[0,1]
	v_pk_fma_f32 v[80:81], v[4:5], v[82:83], v[110:111]
	v_pk_mul_f32 v[82:83], v[74:75], v[102:103] op_sel_hi:[0,1]
	v_pk_mul_f32 v[98:99], v[74:75], v[108:109] op_sel_hi:[0,1]
	v_pk_fma_f32 v[82:83], v[6:7], v[82:83], v[68:69]
	v_pk_mul_f32 v[68:69], v[74:75], v[112:113] op_sel_hi:[0,1]
	v_pk_fma_f32 v[70:71], v[10:11], v[98:99], v[70:71]
	v_pk_mul_f32 v[98:99], v[74:75], v[114:115] op_sel_hi:[0,1]
	v_pk_mul_f32 v[74:75], v[74:75], v[96:97] op_sel_hi:[0,1]
	v_pk_fma_f32 v[68:69], v[8:9], v[68:69], v[116:117]
	v_pk_fma_f32 v[72:73], v[12:13], v[98:99], v[72:73]
	s_and_b64 vcc, exec, s[4:5]
	v_pk_fma_f32 v[74:75], v[14:15], v[74:75], v[104:105]
	s_cbranch_vccz .Lrp352_n2_2
	v_mov_b32_e32 v90, 1.0
	s_branch .Lrp352_st_2

.Lrp352_st_2:
	v_ashrrev_i32_e32 v87, 31, v86
	v_lshlrev_b64 v[86:87], 11, v[86:87]
	v_lshl_add_u64 v[92:93], v[56:57], 0, v[86:87]
	v_cvt_pk_bf16_f32 v94, v76, v77
	v_cvt_pk_bf16_f32 v95, v78, v79
	global_store_dwordx2 v[92:93], v[94:95], off
	v_cvt_pk_bf16_f32 v94, v80, v81
	v_cvt_pk_bf16_f32 v95, v82, v83
	global_store_dwordx2 v[92:93], v[94:95], off offset:512
	v_cvt_pk_bf16_f32 v94, v68, v69
	v_cvt_pk_bf16_f32 v95, v70, v71
	global_store_dwordx2 v[92:93], v[94:95], off offset:1024
	v_cvt_pk_bf16_f32 v94, v72, v73
	v_cvt_pk_bf16_f32 v95, v74, v75
	v_pk_mul_f32 v[76:77], v[76:77], v[90:91] op_sel_hi:[1,0]
	v_pk_mul_f32 v[78:79], v[78:79], v[90:91] op_sel_hi:[1,0]
	v_pk_mul_f32 v[80:81], v[80:81], v[90:91] op_sel_hi:[1,0]
	v_pk_mul_f32 v[82:83], v[82:83], v[90:91] op_sel_hi:[1,0]
	v_pk_mul_f32 v[68:69], v[68:69], v[90:91] op_sel_hi:[1,0]
	v_pk_mul_f32 v[70:71], v[70:71], v[90:91] op_sel_hi:[1,0]
	v_pk_mul_f32 v[72:73], v[72:73], v[90:91] op_sel_hi:[1,0]
	v_pk_mul_f32 v[74:75], v[74:75], v[90:91] op_sel_hi:[1,0]
	v_pk_mul_f32 v[76:77], v[16:17], v[76:77]
	v_pk_mul_f32 v[78:79], v[18:19], v[78:79]
	v_pk_mul_f32 v[80:81], v[20:21], v[80:81]
	v_pk_mul_f32 v[82:83], v[22:23], v[82:83]
	v_pk_mul_f32 v[68:69], v[24:25], v[68:69]
	v_pk_mul_f32 v[70:71], v[26:27], v[70:71]
	v_pk_mul_f32 v[72:73], v[28:29], v[72:73]
	v_pk_mul_f32 v[74:75], v[30:31], v[74:75]
	v_lshl_add_u64 v[86:87], v[50:51], 0, v[86:87]
	v_cvt_pk_bf16_f32 v76, v76, v77
	v_cvt_pk_bf16_f32 v77, v78, v79
	v_cvt_pk_bf16_f32 v80, v80, v81
	v_cvt_pk_bf16_f32 v81, v82, v83
	v_cvt_pk_bf16_f32 v68, v68, v69
	v_cvt_pk_bf16_f32 v69, v70, v71
	v_cvt_pk_bf16_f32 v72, v72, v73
	v_cvt_pk_bf16_f32 v73, v74, v75
	global_store_dwordx2 v[92:93], v[94:95], off offset:1536
	global_store_dwordx2 v[86:87], v[76:77], off
	global_store_dwordx2 v[86:87], v[80:81], off offset:512
	global_store_dwordx2 v[86:87], v[68:69], off offset:1024
	global_store_dwordx2 v[86:87], v[72:73], off offset:1536
	v_subrev_u32_e32 v86, s70, v33
	v_cmp_lt_i32_e32 vcc, v125, v86
	s_or_b64 s[6:7], vcc, s[6:7]
	s_andn2_b64 exec, exec, s[6:7]
	s_cbranch_execz .LBB0_354
	s_branch .LBB0_352

.LBB0_355:
	s_andn2_b64 vcc, exec, s[2:3]
	s_cbranch_vccnz .LBB0_362
	v_mov_b32_e32 v0, v204
	v_cmp_gt_i32_e32 vcc, v124, v32
	s_and_saveexec_b64 s[2:3], vcc
	s_cbranch_execz .LBB0_361
	v_ashrrev_i32_e32 v33, 31, v32
	v_readlane_b32 s4, v254, 32
	v_lshlrev_b32_e32 v0, 2, v0
	v_lshlrev_b64 v[2:3], 11, v[32:33]
	v_readlane_b32 s5, v254, 33
	v_and_b32_e32 v6, 0xfc, v0
	v_lshlrev_b32_e32 v188, 1, v6
	v_lshl_add_u64 v[4:5], s[4:5], 0, v[2:3]
	v_lshl_add_u64 v[2:3], s[88:89], 0, v[2:3]
	v_readlane_b32 s6, v254, 8
	v_lshl_add_u64 v[0:1], v[4:5], 0, v[188:189]
	v_lshl_add_u64 v[2:3], v[2:3], 0, v[188:189]
	v_lshlrev_b32_e32 v38, 2, v6
	v_readlane_b32 s7, v254, 9
	v_add_u32_e32 v22, s70, v32
	global_load_dwordx2 v[34:35], v[0:1], off
	global_load_dwordx2 v[20:21], v[0:1], off offset:512
	global_load_dwordx2 v[18:19], v[0:1], off offset:1024
	global_load_dwordx2 v[16:17], v[0:1], off offset:1536
	global_load_dwordx2 v[70:71], v[2:3], off
	global_load_dwordx2 v[68:69], v[2:3], off offset:512
	global_load_dwordx2 v[66:67], v[2:3], off offset:1024
	global_load_dwordx2 v[64:65], v[2:3], off offset:1536
	v_cmp_gt_i32_e32 vcc, v124, v22
	global_load_dwordx4 v[0:3], v38, s[6:7]
	v_readlane_b32 s6, v254, 10
	v_readlane_b32 s7, v254, 11
	v_cndmask_b32_e32 v22, v32, v22, vcc
	v_ashrrev_i32_e32 v23, 31, v22
	v_lshlrev_b64 v[30:31], 11, v[22:23]
	v_lshl_add_u64 v[22:23], s[88:89], 0, v[30:31]
	v_lshl_add_u64 v[30:31], s[4:5], 0, v[30:31]
	global_load_dwordx4 v[4:7], v38, s[6:7]
	v_readlane_b32 s6, v254, 12
	v_readlane_b32 s7, v254, 13
	v_lshl_add_u64 v[28:29], v[22:23], 0, v[188:189]
	v_lshl_add_u64 v[30:31], v[30:31], 0, v[188:189]
	v_mov_b32_e32 v39, v189
	v_lshl_add_u64 v[36:37], s[88:89], 0, v[188:189]
	s_nop 0
	global_load_dwordx4 v[8:11], v38, s[6:7]
	v_readlane_b32 s6, v254, 14
	v_readlane_b32 s7, v254, 15
	s_nop 4
	global_load_dwordx4 v[12:15], v38, s[6:7]
	global_load_dwordx2 v[22:23], v[28:29], off offset:1536
	global_load_dwordx2 v[24:25], v[28:29], off offset:1024
	global_load_dwordx2 v[26:27], v[28:29], off offset:512
	s_nop 0
	global_load_dwordx2 v[28:29], v[28:29], off
	s_nop 0
	global_load_dwordx2 v[40:41], v[30:31], off offset:1536
	global_load_dwordx2 v[42:43], v[30:31], off offset:1024
	global_load_dwordx2 v[44:45], v[30:31], off offset:512
	global_load_dwordx2 v[46:47], v[30:31], off
	v_readlane_b32 s6, v254, 16
	v_readlane_b32 s7, v254, 17
	v_lshl_add_u64 v[30:31], s[4:5], 0, v[188:189]
	v_lshl_add_u64 v[38:39], s[46:47], 0, v[38:39]
	s_mov_b64 s[4:5], 0
	s_branch .LBB0_359
.LBB0_358:
	v_subrev_u32_e32 v32, s70, v80
	v_cmp_lt_i32_e32 vcc, v125, v32
	s_or_b64 s[4:5], vcc, s[4:5]
	v_mov_b64_e32 v[34:35], v[46:47]
	v_mov_b64_e32 v[20:21], v[44:45]
	v_mov_b64_e32 v[18:19], v[42:43]
	v_mov_b64_e32 v[16:17], v[40:41]
	v_mov_b64_e32 v[70:71], v[28:29]
	v_mov_b64_e32 v[68:69], v[26:27]
	v_mov_b64_e32 v[66:67], v[24:25]
	v_mov_b64_e32 v[64:65], v[22:23]
	v_mov_b64_e32 v[46:47], v[48:49]
	v_mov_b64_e32 v[44:45], v[50:51]
	v_mov_b64_e32 v[42:43], v[52:53]
	v_mov_b64_e32 v[40:41], v[54:55]
	v_mov_b64_e32 v[28:29], v[56:57]
	v_mov_b64_e32 v[26:27], v[58:59]
	v_mov_b64_e32 v[24:25], v[60:61]
	v_mov_b64_e32 v[22:23], v[62:63]
	s_andn2_b64 exec, exec, s[4:5]
	s_cbranch_execz .LBB0_361
.LBB0_359:
	v_add_u32_e32 v80, s71, v32
	v_cmp_gt_i32_e32 vcc, v124, v80
	s_nop 1
	v_cndmask_b32_e32 v48, v32, v80, vcc
	v_ashrrev_i32_e32 v49, 31, v48
	v_lshlrev_b64 v[48:49], 11, v[48:49]
	v_lshl_add_u64 v[54:55], v[30:31], 0, v[48:49]
	v_lshl_add_u64 v[62:63], v[36:37], 0, v[48:49]
	global_load_dwordx2 v[48:49], v[54:55], off
	global_load_dwordx2 v[50:51], v[54:55], off offset:512
	global_load_dwordx2 v[52:53], v[54:55], off offset:1024
	s_nop 0
	global_load_dwordx2 v[54:55], v[54:55], off offset:1536
	s_nop 0
	global_load_dwordx2 v[56:57], v[62:63], off
	global_load_dwordx2 v[58:59], v[62:63], off offset:512
	global_load_dwordx2 v[60:61], v[62:63], off offset:1024
	s_nop 0
	global_load_dwordx2 v[62:63], v[62:63], off offset:1536
	s_waitcnt vmcnt(0)
	v_lshlrev_b32_e32 v78, 16, v70
	v_and_b32_e32 v79, 0xffff0000, v70
	v_lshlrev_b32_e32 v76, 16, v71
	v_and_b32_e32 v77, 0xffff0000, v71
	v_pk_mul_f32 v[82:83], v[78:79], v[78:79]
	v_pk_mul_f32 v[84:85], v[76:77], v[76:77]
	v_add_f32_e32 v33, v82, v83
	v_lshlrev_b32_e32 v74, 16, v68
	v_and_b32_e32 v75, 0xffff0000, v68
	v_add_f32_e32 v33, v84, v33
	v_pk_mul_f32 v[86:87], v[74:75], v[74:75]
	v_add_f32_e32 v33, v85, v33
	v_lshlrev_b32_e32 v72, 16, v69
	v_and_b32_e32 v73, 0xffff0000, v69
	v_add_f32_e32 v33, v86, v33
	v_pk_mul_f32 v[88:89], v[72:73], v[72:73]
	v_add_f32_e32 v33, v87, v33
	v_lshlrev_b32_e32 v70, 16, v66
	v_and_b32_e32 v71, 0xffff0000, v66
	v_add_f32_e32 v33, v88, v33
	v_pk_mul_f32 v[90:91], v[70:71], v[70:71]
	v_add_f32_e32 v33, v89, v33
	v_lshlrev_b32_e32 v68, 16, v67
	v_and_b32_e32 v69, 0xffff0000, v67
	v_add_f32_e32 v33, v90, v33
	v_pk_mul_f32 v[92:93], v[68:69], v[68:69]
	v_add_f32_e32 v33, v91, v33
	v_lshlrev_b32_e32 v66, 16, v64
	v_and_b32_e32 v67, 0xffff0000, v64
	v_add_f32_e32 v33, v92, v33
	v_pk_mul_f32 v[94:95], v[66:67], v[66:67]
	v_add_f32_e32 v33, v93, v33
	s_waitcnt lgkmcnt(0)
	v_and_b32_e32 v81, 64, v207
	v_lshlrev_b32_e32 v64, 16, v65
	v_and_b32_e32 v65, 0xffff0000, v65
	v_add_f32_e32 v33, v94, v33
	v_add_u32_e32 v81, 64, v81
	v_xor_b32_e32 v82, 32, v207
	v_pk_mul_f32 v[96:97], v[64:65], v[64:65]
	v_add_f32_e32 v33, v95, v33
	v_cmp_lt_i32_e32 vcc, v82, v81
	v_add_f32_e32 v33, v96, v33
	v_add_f32_e32 v33, v97, v33
	v_cndmask_b32_e32 v82, v207, v82, vcc
	v_lshlrev_b32_e32 v82, 2, v82
	ds_bpermute_b32 v82, v82, v33
	s_waitcnt lgkmcnt(0)
	v_add_f32_e32 v33, v33, v82
	v_xor_b32_e32 v82, 16, v207
	v_cmp_lt_i32_e32 vcc, v82, v81
	s_nop 1
	v_cndmask_b32_e32 v82, v207, v82, vcc
	v_lshlrev_b32_e32 v82, 2, v82
	ds_bpermute_b32 v82, v82, v33
	s_waitcnt lgkmcnt(0)
	v_add_f32_e32 v33, v33, v82
	v_xor_b32_e32 v82, 8, v207
	v_cmp_lt_i32_e32 vcc, v82, v81
	s_nop 1
	v_cndmask_b32_e32 v82, v207, v82, vcc
	v_lshlrev_b32_e32 v82, 2, v82
	ds_bpermute_b32 v82, v82, v33
	s_waitcnt lgkmcnt(0)
	v_add_f32_e32 v33, v33, v82
	v_xor_b32_e32 v82, 4, v207
	v_cmp_lt_i32_e32 vcc, v82, v81
	s_nop 1
	v_cndmask_b32_e32 v82, v207, v82, vcc
	v_lshlrev_b32_e32 v82, 2, v82
	ds_bpermute_b32 v82, v82, v33
	s_waitcnt lgkmcnt(0)
	v_add_f32_e32 v33, v33, v82
	v_xor_b32_e32 v82, 2, v207
	v_cmp_lt_i32_e32 vcc, v82, v81
	s_nop 1
	v_cndmask_b32_e32 v82, v207, v82, vcc
	v_lshlrev_b32_e32 v82, 2, v82
	ds_bpermute_b32 v82, v82, v33
	s_waitcnt lgkmcnt(0)
	v_add_f32_e32 v33, v33, v82
	v_xor_b32_e32 v82, 1, v207
	v_cmp_lt_i32_e32 vcc, v82, v81
	s_nop 1
	v_cndmask_b32_e32 v81, v207, v82, vcc
	v_lshlrev_b32_e32 v81, 2, v81
	ds_bpermute_b32 v81, v81, v33
	s_andn2_b64 vcc, exec, s[6:7]
	s_cbranch_vccnz .LBB0_358
	s_waitcnt lgkmcnt(0)
	v_add_f32_e32 v33, v33, v81
	v_fmamk_f32 v33, v33, 0x3a800000, v205
	v_mul_f32_e32 v81, 0x4b800000, v33
	v_cmp_gt_f32_e32 vcc, s30, v33
	s_nop 1
	v_cndmask_b32_e32 v33, v33, v81, vcc
	v_rsq_f32_e32 v81, v33
	v_ashrrev_i32_e32 v33, 31, v32
	v_lshlrev_b64 v[32:33], 12, v[32:33]
	v_lshl_add_u64 v[84:85], v[38:39], 0, v[32:33]
	v_mul_f32_e32 v82, 0x45800000, v81
	v_cndmask_b32_e32 v82, v81, v82, vcc
	v_pk_mul_f32 v[32:33], v[82:83], v[78:79] op_sel_hi:[0,1]
	v_lshlrev_b32_e32 v78, 16, v34
	v_and_b32_e32 v79, 0xffff0000, v34
	v_pk_mul_f32 v[76:77], v[82:83], v[76:77] op_sel_hi:[0,1]
	v_lshlrev_b32_e32 v34, 16, v35
	v_and_b32_e32 v35, 0xffff0000, v35
	v_pk_fma_f32 v[32:33], v[0:1], v[32:33], v[78:79]
	v_pk_fma_f32 v[34:35], v[2:3], v[76:77], v[34:35]
	global_store_dwordx4 v[84:85], v[32:35], off
	s_nop 1
	v_pk_mul_f32 v[32:33], v[82:83], v[74:75] op_sel_hi:[0,1]
	v_lshlrev_b32_e32 v34, 16, v20
	v_and_b32_e32 v35, 0xffff0000, v20
	v_pk_fma_f32 v[32:33], v[4:5], v[32:33], v[34:35]
	v_pk_mul_f32 v[34:35], v[82:83], v[72:73] op_sel_hi:[0,1]
	v_lshlrev_b32_e32 v20, 16, v21
	v_and_b32_e32 v21, 0xffff0000, v21
	v_pk_fma_f32 v[34:35], v[6:7], v[34:35], v[20:21]
	global_store_dwordx4 v[84:85], v[32:35], off offset:1024
	v_pk_mul_f32 v[20:21], v[82:83], v[70:71] op_sel_hi:[0,1]
	s_nop 0
	v_lshlrev_b32_e32 v32, 16, v18
	v_and_b32_e32 v33, 0xffff0000, v18
	v_pk_fma_f32 v[32:33], v[8:9], v[20:21], v[32:33]
	v_pk_mul_f32 v[20:21], v[82:83], v[68:69] op_sel_hi:[0,1]
	v_lshlrev_b32_e32 v18, 16, v19
	v_and_b32_e32 v19, 0xffff0000, v19
	v_pk_fma_f32 v[34:35], v[10:11], v[20:21], v[18:19]
	v_pk_mul_f32 v[18:19], v[82:83], v[66:67] op_sel_hi:[0,1]
	v_lshlrev_b32_e32 v20, 16, v16
	v_and_b32_e32 v21, 0xffff0000, v16
	v_pk_fma_f32 v[18:19], v[12:13], v[18:19], v[20:21]
	v_pk_mul_f32 v[20:21], v[82:83], v[64:65] op_sel_hi:[0,1]
	v_lshlrev_b32_e32 v16, 16, v17
	v_and_b32_e32 v17, 0xffff0000, v17
	v_pk_fma_f32 v[20:21], v[14:15], v[20:21], v[16:17]
	global_store_dwordx4 v[84:85], v[32:35], off offset:2048
	global_store_dwordx4 v[84:85], v[18:21], off offset:3072
	s_branch .LBB0_358

.Lp2b_done:
	v_ashrrev_i32_e32 v0, 6, v0
	v_readlane_b32 s2, v254, 49
	v_add_u32_e32 v20, s69, v0
	s_cmp_eq_u32 s70, 1
	s_cbranch_scc0 .Lrm9_old
	v_lshlrev_b32_e32 v20, 4, v20
.Lrm9_old:
	s_mov_b32 s0, s2
	v_readlane_b32 s3, v254, 50
	v_readlane_b32 s2, v254, 6
	v_readlane_b32 s3, v254, 7
	v_mov_b32_e32 v32, 1.0
	v_mov_b32_e32 v33, 1.0
	v_mov_b32_e32 v34, 1.0
	v_mov_b32_e32 v35, 1.0
	v_mov_b32_e32 v36, 1.0
	v_mov_b32_e32 v37, 1.0
	v_mov_b32_e32 v38, 1.0
	v_mov_b32_e32 v39, 1.0
	v_mov_b32_e32 v40, 1.0
	v_mov_b32_e32 v41, 1.0
	v_mov_b32_e32 v42, 1.0
	v_mov_b32_e32 v43, 1.0
	v_mov_b32_e32 v44, 1.0
	v_mov_b32_e32 v45, 1.0
	v_mov_b32_e32 v46, 1.0
	v_mov_b32_e32 v47, 1.0
	v_and_b32_e32 v30, 63, v204
	v_lshlrev_b32_e32 v30, 4, v30
	s_andn2_b64 vcc, exec, s[2:3]
	s_cbranch_vccnz .Lrp0_nogain
	v_readlane_b32 s8, v252, 12
	v_readlane_b32 s9, v252, 13
	s_nop 4
	global_load_dwordx4 v[32:35], v30, s[8:9]
	global_load_dwordx4 v[36:39], v30, s[8:9] offset:1024
	global_load_dwordx4 v[40:43], v30, s[8:9] offset:2048
	global_load_dwordx4 v[44:47], v30, s[8:9] offset:3072
